# EpiWin forget-gate class: drop the never-taken subnormal-rescale arm of the log expansion and the self-max before the clamp (log argument >= 8.7e-27)
# speedup vs baseline: 1.0117x; 1.0018x over previous
.LBB0_552:
	s_andn2_b64 vcc, exec, s[10:11]
	s_cbranch_vccnz .LBB0_554
	v_lshl_add_u32 v156, s93, 8, v194
	v_ashrrev_i32_e32 v157, 31, v156
	v_lshlrev_b64 v[158:159], 2, v[156:157]
	v_lshl_add_u64 v[126:127], s[80:81], 0, v[158:159]
	global_load_dwordx4 v[122:125], v[126:127], off offset:16
	s_nop 0
	global_load_dwordx4 v[126:129], v[126:127], off
	s_mov_b32 s14, 0xc2700000
	v_med3_f32 v96, v164, s14, v231
	v_mul_f32_e32 v96, 0xbfb8aa3b, v96
	v_exp_f32_e32 v160, v96
	s_mov_b32 s1, 0x3f317217
	v_lshl_add_u64 v[158:159], v[154:155], 0, v[158:159]
	v_add_f32_e32 v96, 1.0, v160
	v_rcp_f32_e32 v162, v96
	v_med3_f32 v96, v165, s14, v231
	v_mul_f32_e32 v96, 0xbfb8aa3b, v96
	v_exp_f32_e32 v161, v96
	s_waitcnt vmcnt(0)
	v_pk_add_f32 v[180:181], v[122:123], 1.0 op_sel_hi:[1,0] neg_lo:[1,0] neg_hi:[1,0]
	v_add_f32_e32 v96, 1.0, v161
	v_pk_add_f32 v[174:175], v[126:127], 1.0 op_sel_hi:[1,0] neg_lo:[1,0] neg_hi:[1,0]
	v_rcp_f32_e32 v163, v96
	v_fma_f32 v96, v162, v174, v126
	v_pk_add_f32 v[178:179], v[128:129], 1.0 op_sel_hi:[1,0] neg_lo:[1,0] neg_hi:[1,0]
	v_pk_mul_f32 v[160:161], v[160:161], v[162:163]
	v_log_f32_e32 v96, v96
	v_pk_mul_f32 v[160:161], v[160:161], v[174:175]
	v_pk_add_f32 v[182:183], v[124:125], 1.0 op_sel_hi:[1,0] neg_lo:[1,0] neg_hi:[1,0]
	v_mul_f32_e32 v126, 0x3f317217, v96
	v_fma_f32 v126, v96, s1, -v126
	v_fmac_f32_e32 v126, 0x3377d1cf, v96
	v_fmac_f32_e32 v126, 0x3f317217, v96
	v_cmp_lt_f32_e64 s[10:11], |v96|, s4
	s_nop 1
	v_cndmask_b32_e64 v96, v96, v126, s[10:11]
	v_mov_b32_e32 v126, v96
	v_fma_f32 v96, v163, v175, v127
	v_log_f32_e32 v96, v96
	s_nop 0
	v_mul_f32_e32 v127, 0x3f317217, v96
	v_fma_f32 v127, v96, s1, -v127
	v_fmac_f32_e32 v127, 0x3377d1cf, v96
	v_fmac_f32_e32 v127, 0x3f317217, v96
	v_cmp_lt_f32_e64 s[10:11], |v96|, s4
	s_nop 1
	v_cndmask_b32_e64 v96, v96, v127, s[10:11]
	v_mov_b32_e32 v127, v96
	v_med3_f32 v96, v166, s14, v231
	v_mul_f32_e32 v96, 0xbfb8aa3b, v96
	v_exp_f32_e32 v162, v96
	s_nop 0
	v_add_f32_e32 v96, 1.0, v162
	v_rcp_f32_e32 v174, v96
	v_med3_f32 v96, v167, s14, v231
	v_mul_f32_e32 v96, 0xbfb8aa3b, v96
	v_exp_f32_e32 v163, v96
	s_nop 0
	v_add_f32_e32 v96, 1.0, v163
	v_rcp_f32_e32 v175, v96
	v_fma_f32 v96, v174, v178, v128
	v_fmac_f32_e32 v129, v175, v179
	v_log_f32_e32 v96, v96
	v_pk_mul_f32 v[162:163], v[162:163], v[174:175]
	v_mul_f32_e32 v128, 0x3f317217, v96
	v_fma_f32 v128, v96, s1, -v128
	v_fmac_f32_e32 v128, 0x3377d1cf, v96
	v_fmac_f32_e32 v128, 0x3f317217, v96
	v_cmp_lt_f32_e64 s[10:11], |v96|, s4
	v_pk_mul_f32 v[162:163], v[162:163], v[178:179]
	s_nop 0
	v_cndmask_b32_e64 v96, v96, v128, s[10:11]
	v_mov_b32_e32 v128, v96
	v_mov_b32_e32 v96, v129
	v_log_f32_e32 v96, v96
	s_nop 0
	v_mul_f32_e32 v129, 0x3f317217, v96
	v_fma_f32 v129, v96, s1, -v129
	v_fmac_f32_e32 v129, 0x3377d1cf, v96
	v_fmac_f32_e32 v129, 0x3f317217, v96
	v_cmp_lt_f32_e64 s[10:11], |v96|, s4
	s_nop 1
	v_cndmask_b32_e64 v96, v96, v129, s[10:11]
	v_mov_b32_e32 v129, v96
	v_med3_f32 v96, v168, s14, v231
	v_mul_f32_e32 v96, 0xbfb8aa3b, v96
	v_exp_f32_e32 v178, v96
	s_nop 0
	v_add_f32_e32 v96, 1.0, v178
	v_rcp_f32_e32 v174, v96
	v_med3_f32 v96, v169, s14, v231
	v_mul_f32_e32 v96, 0xbfb8aa3b, v96
	v_exp_f32_e32 v179, v96
	s_nop 0
	v_add_f32_e32 v96, 1.0, v179
	v_rcp_f32_e32 v175, v96
	v_fma_f32 v96, v174, v180, v122
	v_pk_mul_f32 v[178:179], v[178:179], v[174:175]
	v_log_f32_e32 v96, v96
	v_pk_mul_f32 v[178:179], v[178:179], v[180:181]
	v_mul_f32_e32 v122, 0x3f317217, v96
	v_fma_f32 v122, v96, s1, -v122
	v_fmac_f32_e32 v122, 0x3377d1cf, v96
	v_fmac_f32_e32 v122, 0x3f317217, v96
	v_cmp_lt_f32_e64 s[10:11], |v96|, s4
	s_nop 1
	v_cndmask_b32_e64 v96, v96, v122, s[10:11]
	v_mov_b32_e32 v122, v96
	v_fma_f32 v96, v175, v181, v123
	v_log_f32_e32 v96, v96
	s_nop 0
	v_mul_f32_e32 v123, 0x3f317217, v96
	v_fma_f32 v123, v96, s1, -v123
	v_fmac_f32_e32 v123, 0x3377d1cf, v96
	v_fmac_f32_e32 v123, 0x3f317217, v96
	v_cmp_lt_f32_e64 s[10:11], |v96|, s4
	s_nop 1
	v_cndmask_b32_e64 v96, v96, v123, s[10:11]
	v_mov_b32_e32 v123, v96
	v_med3_f32 v96, v176, s14, v231
	v_mul_f32_e32 v96, 0xbfb8aa3b, v96
	v_exp_f32_e32 v174, v96
	s_nop 0
	v_add_f32_e32 v96, 1.0, v174
	v_rcp_f32_e32 v180, v96
	v_med3_f32 v96, v177, s14, v231
	v_mul_f32_e32 v96, 0xbfb8aa3b, v96
	v_exp_f32_e32 v175, v96
	s_nop 0
	v_add_f32_e32 v96, 1.0, v175
	v_rcp_f32_e32 v181, v96
	v_fma_f32 v96, v180, v182, v124
	v_fmac_f32_e32 v125, v181, v183
	v_log_f32_e32 v96, v96
	v_pk_mul_f32 v[174:175], v[174:175], v[180:181]
	v_mul_f32_e32 v124, 0x3f317217, v96
	v_fma_f32 v124, v96, s1, -v124
	v_fmac_f32_e32 v124, 0x3377d1cf, v96
	v_fmac_f32_e32 v124, 0x3f317217, v96
	v_cmp_lt_f32_e64 s[10:11], |v96|, s4
	v_pk_mul_f32 v[174:175], v[174:175], v[182:183]
	s_nop 0
	v_cndmask_b32_e64 v96, v96, v124, s[10:11]
	v_mov_b32_e32 v124, v96
	v_mov_b32_e32 v96, v125
	v_log_f32_e32 v96, v96
	s_nop 0
	v_mul_f32_e32 v125, 0x3f317217, v96
	v_fma_f32 v125, v96, s1, -v125
	v_fmac_f32_e32 v125, 0x3377d1cf, v96
	v_fmac_f32_e32 v125, 0x3f317217, v96
	v_cmp_lt_f32_e64 s[10:11], |v96|, s4
	s_nop 1
	v_cndmask_b32_e64 v96, v96, v125, s[10:11]
	v_mov_b32_e32 v125, v96
	global_store_dwordx4 v[158:159], v[126:129], off
	global_store_dwordx4 v[158:159], v[122:125], off offset:16
	s_nop 0
	v_lshl_add_u64 v[126:127], v[156:157], 1, v[152:153]
	v_cvt_pk_bf16_f32 v122, v160, v161
	v_cvt_pk_bf16_f32 v123, v162, v163
	v_cvt_pk_bf16_f32 v124, v178, v179
	v_cvt_pk_bf16_f32 v125, v174, v175
	global_store_dwordx4 v[126:127], v[122:125], off

.LBB0_584:
	s_andn2_b64 vcc, exec, s[10:11]
	s_cbranch_vccnz .LBB0_586
	v_lshl_add_u32 v172, s95, 7, v194
	v_ashrrev_i32_e32 v173, 31, v172
	v_lshlrev_b64 v[176:177], 2, v[172:173]
	v_lshl_add_u64 v[118:119], s[80:81], 0, v[176:177]
	global_load_dwordx4 v[114:117], v[118:119], off offset:16
	s_nop 0
	global_load_dwordx4 v[118:121], v[118:119], off
	s_mov_b32 s17, 0xc2700000
	v_med3_f32 v96, v164, s17, v231
	v_mul_f32_e32 v96, 0xbfb8aa3b, v96
	v_exp_f32_e32 v178, v96
	s_mov_b32 s1, 0x3f317217
	v_lshl_add_u64 v[154:155], v[154:155], 0, v[176:177]
	v_add_f32_e32 v96, 1.0, v178
	v_rcp_f32_e32 v180, v96
	v_med3_f32 v96, v165, s17, v231
	v_mul_f32_e32 v96, 0xbfb8aa3b, v96
	v_exp_f32_e32 v179, v96
	s_waitcnt vmcnt(0)
	v_pk_add_f32 v[186:187], v[114:115], 1.0 op_sel_hi:[1,0] neg_lo:[1,0] neg_hi:[1,0]
	v_add_f32_e32 v96, 1.0, v179
	v_pk_add_f32 v[182:183], v[118:119], 1.0 op_sel_hi:[1,0] neg_lo:[1,0] neg_hi:[1,0]
	v_rcp_f32_e32 v181, v96
	v_fma_f32 v96, v180, v182, v118
	v_pk_add_f32 v[184:185], v[120:121], 1.0 op_sel_hi:[1,0] neg_lo:[1,0] neg_hi:[1,0]
	v_pk_mul_f32 v[178:179], v[178:179], v[180:181]
	v_log_f32_e32 v96, v96
	v_pk_mul_f32 v[178:179], v[178:179], v[182:183]
	v_pk_add_f32 v[210:211], v[116:117], 1.0 op_sel_hi:[1,0] neg_lo:[1,0] neg_hi:[1,0]
	v_mul_f32_e32 v118, 0x3f317217, v96
	v_fma_f32 v118, v96, s1, -v118
	v_fmac_f32_e32 v118, 0x3377d1cf, v96
	v_fmac_f32_e32 v118, 0x3f317217, v96
	v_cmp_lt_f32_e64 s[10:11], |v96|, s4
	s_nop 1
	v_cndmask_b32_e64 v96, v96, v118, s[10:11]
	v_mov_b32_e32 v118, v96
	v_fma_f32 v96, v181, v183, v119
	v_log_f32_e32 v96, v96
	s_nop 0
	v_mul_f32_e32 v119, 0x3f317217, v96
	v_fma_f32 v119, v96, s1, -v119
	v_fmac_f32_e32 v119, 0x3377d1cf, v96
	v_fmac_f32_e32 v119, 0x3f317217, v96
	v_cmp_lt_f32_e64 s[10:11], |v96|, s4
	s_nop 1
	v_cndmask_b32_e64 v96, v96, v119, s[10:11]
	v_mov_b32_e32 v119, v96
	v_med3_f32 v96, v166, s17, v231
	v_mul_f32_e32 v96, 0xbfb8aa3b, v96
	v_exp_f32_e32 v180, v96
	s_nop 0
	v_add_f32_e32 v96, 1.0, v180
	v_rcp_f32_e32 v182, v96
	v_med3_f32 v96, v167, s17, v231
	v_mul_f32_e32 v96, 0xbfb8aa3b, v96
	v_exp_f32_e32 v181, v96
	s_nop 0
	v_add_f32_e32 v96, 1.0, v181
	v_rcp_f32_e32 v183, v96
	v_fma_f32 v96, v182, v184, v120
	v_fmac_f32_e32 v121, v183, v185
	v_log_f32_e32 v96, v96
	v_pk_mul_f32 v[180:181], v[180:181], v[182:183]
	v_mul_f32_e32 v120, 0x3f317217, v96
	v_fma_f32 v120, v96, s1, -v120
	v_fmac_f32_e32 v120, 0x3377d1cf, v96
	v_fmac_f32_e32 v120, 0x3f317217, v96
	v_cmp_lt_f32_e64 s[10:11], |v96|, s4
	v_pk_mul_f32 v[180:181], v[180:181], v[184:185]
	s_nop 0
	v_cndmask_b32_e64 v96, v96, v120, s[10:11]
	v_mov_b32_e32 v120, v96
	v_mov_b32_e32 v96, v121
	v_log_f32_e32 v96, v96
	s_nop 0
	v_mul_f32_e32 v121, 0x3f317217, v96
	v_fma_f32 v121, v96, s1, -v121
	v_fmac_f32_e32 v121, 0x3377d1cf, v96
	v_fmac_f32_e32 v121, 0x3f317217, v96
	v_cmp_lt_f32_e64 s[10:11], |v96|, s4
	s_nop 1
	v_cndmask_b32_e64 v96, v96, v121, s[10:11]
	v_mov_b32_e32 v121, v96
	v_med3_f32 v96, v168, s17, v231
	v_mul_f32_e32 v96, 0xbfb8aa3b, v96
	v_exp_f32_e32 v184, v96
	s_nop 0
	v_add_f32_e32 v96, 1.0, v184
	v_rcp_f32_e32 v182, v96
	v_med3_f32 v96, v169, s17, v231
	v_mul_f32_e32 v96, 0xbfb8aa3b, v96
	v_exp_f32_e32 v185, v96
	s_nop 0
	v_add_f32_e32 v96, 1.0, v185
	v_rcp_f32_e32 v183, v96
	v_fma_f32 v96, v182, v186, v114
	v_pk_mul_f32 v[184:185], v[184:185], v[182:183]
	v_log_f32_e32 v96, v96
	v_pk_mul_f32 v[184:185], v[184:185], v[186:187]
	v_mul_f32_e32 v114, 0x3f317217, v96
	v_fma_f32 v114, v96, s1, -v114
	v_fmac_f32_e32 v114, 0x3377d1cf, v96
	v_fmac_f32_e32 v114, 0x3f317217, v96
	v_cmp_lt_f32_e64 s[10:11], |v96|, s4
	s_nop 1
	v_cndmask_b32_e64 v96, v96, v114, s[10:11]
	v_mov_b32_e32 v114, v96
	v_fma_f32 v96, v183, v187, v115
	v_log_f32_e32 v96, v96
	s_nop 0
	v_mul_f32_e32 v115, 0x3f317217, v96
	v_fma_f32 v115, v96, s1, -v115
	v_fmac_f32_e32 v115, 0x3377d1cf, v96
	v_fmac_f32_e32 v115, 0x3f317217, v96
	v_cmp_lt_f32_e64 s[10:11], |v96|, s4
	s_nop 1
	v_cndmask_b32_e64 v96, v96, v115, s[10:11]
	v_mov_b32_e32 v115, v96
	v_med3_f32 v96, v170, s17, v231
	v_mul_f32_e32 v96, 0xbfb8aa3b, v96
	v_exp_f32_e32 v182, v96
	s_nop 0
	v_add_f32_e32 v96, 1.0, v182
	v_rcp_f32_e32 v186, v96
	v_med3_f32 v96, v171, s17, v231
	v_mul_f32_e32 v96, 0xbfb8aa3b, v96
	v_exp_f32_e32 v183, v96
	s_nop 0
	v_add_f32_e32 v96, 1.0, v183
	v_rcp_f32_e32 v187, v96
	v_fma_f32 v96, v186, v210, v116
	v_fmac_f32_e32 v117, v187, v211
	v_log_f32_e32 v96, v96
	v_pk_mul_f32 v[182:183], v[182:183], v[186:187]
	v_mul_f32_e32 v116, 0x3f317217, v96
	v_fma_f32 v116, v96, s1, -v116
	v_fmac_f32_e32 v116, 0x3377d1cf, v96
	v_fmac_f32_e32 v116, 0x3f317217, v96
	v_cmp_lt_f32_e64 s[10:11], |v96|, s4
	v_pk_mul_f32 v[182:183], v[182:183], v[210:211]
	s_nop 0
	v_cndmask_b32_e64 v96, v96, v116, s[10:11]
	v_mov_b32_e32 v116, v96
	v_mov_b32_e32 v96, v117
	v_log_f32_e32 v96, v96
	s_nop 0
	v_mul_f32_e32 v117, 0x3f317217, v96
	v_fma_f32 v117, v96, s1, -v117
	v_fmac_f32_e32 v117, 0x3377d1cf, v96
	v_fmac_f32_e32 v117, 0x3f317217, v96
	v_cmp_lt_f32_e64 s[10:11], |v96|, s4
	s_nop 1
	v_cndmask_b32_e64 v96, v96, v117, s[10:11]
	v_mov_b32_e32 v117, v96
	global_store_dwordx4 v[154:155], v[118:121], off
	global_store_dwordx4 v[154:155], v[114:117], off offset:16
	s_nop 0
	v_lshl_add_u64 v[118:119], v[172:173], 1, v[152:153]
	v_cvt_pk_bf16_f32 v114, v178, v179
	v_cvt_pk_bf16_f32 v115, v180, v181
	v_cvt_pk_bf16_f32 v116, v184, v185
	v_cvt_pk_bf16_f32 v117, v182, v183
	global_store_dwordx4 v[118:119], v[114:117], off
	s_mov_b64 s[10:11], 0
	s_branch .LBB0_603

.LBB0_619:
	s_andn2_b64 vcc, exec, s[12:13]
	s_cbranch_vccnz .LBB0_621
	v_lshl_add_u32 v150, s93, 8, v194
	v_ashrrev_i32_e32 v151, 31, v150
	v_lshlrev_b64 v[152:153], 2, v[150:151]
	v_lshl_add_u64 v[110:111], s[80:81], 0, v[152:153]
	global_load_dwordx4 v[106:109], v[110:111], off offset:16
	s_nop 0
	global_load_dwordx4 v[110:113], v[110:111], off
	s_mov_b32 s17, 0xc2700000
	v_med3_f32 v96, v154, s17, v231
	v_mul_f32_e32 v96, 0xbfb8aa3b, v96
	v_exp_f32_e32 v160, v96
	s_mov_b32 s1, 0x3f317217
	v_lshl_add_u64 v[152:153], v[120:121], 0, v[152:153]
	v_add_f32_e32 v96, 1.0, v160
	v_rcp_f32_e32 v168, v96
	v_med3_f32 v96, v155, s17, v231
	v_mul_f32_e32 v96, 0xbfb8aa3b, v96
	v_exp_f32_e32 v161, v96
	s_waitcnt vmcnt(0)
	v_pk_add_f32 v[174:175], v[106:107], 1.0 op_sel_hi:[1,0] neg_lo:[1,0] neg_hi:[1,0]
	v_add_f32_e32 v96, 1.0, v161
	v_pk_add_f32 v[170:171], v[110:111], 1.0 op_sel_hi:[1,0] neg_lo:[1,0] neg_hi:[1,0]
	v_rcp_f32_e32 v169, v96
	v_fma_f32 v96, v168, v170, v110
	v_pk_add_f32 v[172:173], v[112:113], 1.0 op_sel_hi:[1,0] neg_lo:[1,0] neg_hi:[1,0]
	v_pk_mul_f32 v[160:161], v[160:161], v[168:169]
	v_log_f32_e32 v96, v96
	v_pk_mul_f32 v[160:161], v[160:161], v[170:171]
	v_pk_add_f32 v[176:177], v[108:109], 1.0 op_sel_hi:[1,0] neg_lo:[1,0] neg_hi:[1,0]
	v_mul_f32_e32 v110, 0x3f317217, v96
	v_fma_f32 v110, v96, s1, -v110
	v_fmac_f32_e32 v110, 0x3377d1cf, v96
	v_fmac_f32_e32 v110, 0x3f317217, v96
	v_cmp_lt_f32_e64 s[12:13], |v96|, s4
	s_nop 1
	v_cndmask_b32_e64 v96, v96, v110, s[12:13]
	v_mov_b32_e32 v110, v96
	v_fma_f32 v96, v169, v171, v111
	v_log_f32_e32 v96, v96
	s_nop 0
	v_mul_f32_e32 v111, 0x3f317217, v96
	v_fma_f32 v111, v96, s1, -v111
	v_fmac_f32_e32 v111, 0x3377d1cf, v96
	v_fmac_f32_e32 v111, 0x3f317217, v96
	v_cmp_lt_f32_e64 s[12:13], |v96|, s4
	s_nop 1
	v_cndmask_b32_e64 v96, v96, v111, s[12:13]
	v_mov_b32_e32 v111, v96
	v_med3_f32 v96, v162, s17, v231
	v_mul_f32_e32 v96, 0xbfb8aa3b, v96
	v_exp_f32_e32 v168, v96
	s_nop 0
	v_add_f32_e32 v96, 1.0, v168
	v_rcp_f32_e32 v170, v96
	v_med3_f32 v96, v163, s17, v231
	v_mul_f32_e32 v96, 0xbfb8aa3b, v96
	v_exp_f32_e32 v169, v96
	s_nop 0
	v_add_f32_e32 v96, 1.0, v169
	v_rcp_f32_e32 v171, v96
	v_fma_f32 v96, v170, v172, v112
	v_fmac_f32_e32 v113, v171, v173
	v_log_f32_e32 v96, v96
	v_pk_mul_f32 v[168:169], v[168:169], v[170:171]
	v_mul_f32_e32 v112, 0x3f317217, v96
	v_fma_f32 v112, v96, s1, -v112
	v_fmac_f32_e32 v112, 0x3377d1cf, v96
	v_fmac_f32_e32 v112, 0x3f317217, v96
	v_cmp_lt_f32_e64 s[12:13], |v96|, s4
	v_pk_mul_f32 v[168:169], v[168:169], v[172:173]
	s_nop 0
	v_cndmask_b32_e64 v96, v96, v112, s[12:13]
	v_mov_b32_e32 v112, v96
	v_mov_b32_e32 v96, v113
	v_log_f32_e32 v96, v96
	s_nop 0
	v_mul_f32_e32 v113, 0x3f317217, v96
	v_fma_f32 v113, v96, s1, -v113
	v_fmac_f32_e32 v113, 0x3377d1cf, v96
	v_fmac_f32_e32 v113, 0x3f317217, v96
	v_cmp_lt_f32_e64 s[12:13], |v96|, s4
	s_nop 1
	v_cndmask_b32_e64 v96, v96, v113, s[12:13]
	v_mov_b32_e32 v113, v96
	v_med3_f32 v96, v164, s17, v231
	v_mul_f32_e32 v96, 0xbfb8aa3b, v96
	v_exp_f32_e32 v172, v96
	s_nop 0
	v_add_f32_e32 v96, 1.0, v172
	v_rcp_f32_e32 v170, v96
	v_med3_f32 v96, v165, s17, v231
	v_mul_f32_e32 v96, 0xbfb8aa3b, v96
	v_exp_f32_e32 v173, v96
	s_nop 0
	v_add_f32_e32 v96, 1.0, v173
	v_rcp_f32_e32 v171, v96
	v_fma_f32 v96, v170, v174, v106
	v_pk_mul_f32 v[172:173], v[172:173], v[170:171]
	v_log_f32_e32 v96, v96
	v_pk_mul_f32 v[172:173], v[172:173], v[174:175]
	v_mul_f32_e32 v106, 0x3f317217, v96
	v_fma_f32 v106, v96, s1, -v106
	v_fmac_f32_e32 v106, 0x3377d1cf, v96
	v_fmac_f32_e32 v106, 0x3f317217, v96
	v_cmp_lt_f32_e64 s[12:13], |v96|, s4
	s_nop 1
	v_cndmask_b32_e64 v96, v96, v106, s[12:13]
	v_mov_b32_e32 v106, v96
	v_fma_f32 v96, v171, v175, v107
	v_log_f32_e32 v96, v96
	s_nop 0
	v_mul_f32_e32 v107, 0x3f317217, v96
	v_fma_f32 v107, v96, s1, -v107
	v_fmac_f32_e32 v107, 0x3377d1cf, v96
	v_fmac_f32_e32 v107, 0x3f317217, v96
	v_cmp_lt_f32_e64 s[12:13], |v96|, s4
	s_nop 1
	v_cndmask_b32_e64 v96, v96, v107, s[12:13]
	v_mov_b32_e32 v107, v96
	v_med3_f32 v96, v166, s17, v231
	v_mul_f32_e32 v96, 0xbfb8aa3b, v96
	v_exp_f32_e32 v170, v96
	s_nop 0
	v_add_f32_e32 v96, 1.0, v170
	v_rcp_f32_e32 v174, v96
	v_med3_f32 v96, v167, s17, v231
	v_mul_f32_e32 v96, 0xbfb8aa3b, v96
	v_exp_f32_e32 v171, v96
	s_nop 0
	v_add_f32_e32 v96, 1.0, v171
	v_rcp_f32_e32 v175, v96
	v_fma_f32 v96, v174, v176, v108
	v_fmac_f32_e32 v109, v175, v177
	v_log_f32_e32 v96, v96
	v_pk_mul_f32 v[170:171], v[170:171], v[174:175]
	v_mul_f32_e32 v108, 0x3f317217, v96
	v_fma_f32 v108, v96, s1, -v108
	v_fmac_f32_e32 v108, 0x3377d1cf, v96
	v_fmac_f32_e32 v108, 0x3f317217, v96
	v_cmp_lt_f32_e64 s[12:13], |v96|, s4
	v_pk_mul_f32 v[170:171], v[170:171], v[176:177]
	s_nop 0
	v_cndmask_b32_e64 v96, v96, v108, s[12:13]
	v_mov_b32_e32 v108, v96
	v_mov_b32_e32 v96, v109
	v_log_f32_e32 v96, v96
	s_nop 0
	v_mul_f32_e32 v109, 0x3f317217, v96
	v_fma_f32 v109, v96, s1, -v109
	v_fmac_f32_e32 v109, 0x3377d1cf, v96
	v_fmac_f32_e32 v109, 0x3f317217, v96
	v_cmp_lt_f32_e64 s[12:13], |v96|, s4
	s_nop 1
	v_cndmask_b32_e64 v96, v96, v109, s[12:13]
	v_mov_b32_e32 v109, v96
	global_store_dwordx4 v[152:153], v[110:113], off
	global_store_dwordx4 v[152:153], v[106:109], off offset:16
	s_nop 0
	v_lshl_add_u64 v[110:111], v[150:151], 1, v[118:119]
	v_cvt_pk_bf16_f32 v106, v160, v161
	v_cvt_pk_bf16_f32 v107, v168, v169
	v_cvt_pk_bf16_f32 v108, v172, v173
	v_cvt_pk_bf16_f32 v109, v170, v171
	global_store_dwordx4 v[110:111], v[106:109], off

.LBB0_651:
	s_andn2_b64 vcc, exec, s[14:15]
	s_cbranch_vccnz .LBB0_653
	v_lshl_add_u32 v158, s95, 7, v194
	v_ashrrev_i32_e32 v159, 31, v158
	v_lshlrev_b64 v[162:163], 2, v[158:159]
	v_lshl_add_u64 v[102:103], s[80:81], 0, v[162:163]
	global_load_dwordx4 v[98:101], v[102:103], off offset:16
	s_nop 0
	global_load_dwordx4 v[102:105], v[102:103], off
	s_mov_b32 s17, 0xc2700000
	v_med3_f32 v96, v106, s17, v231
	v_mul_f32_e32 v96, 0xbfb8aa3b, v96
	v_exp_f32_e32 v164, v96
	s_mov_b32 s1, 0x3f317217
	v_lshl_add_u64 v[120:121], v[120:121], 0, v[162:163]
	v_add_f32_e32 v96, 1.0, v164
	v_rcp_f32_e32 v166, v96
	v_med3_f32 v96, v107, s17, v231
	v_mul_f32_e32 v96, 0xbfb8aa3b, v96
	v_exp_f32_e32 v165, v96
	s_waitcnt vmcnt(0)
	v_pk_add_f32 v[172:173], v[98:99], 1.0 op_sel_hi:[1,0] neg_lo:[1,0] neg_hi:[1,0]
	v_add_f32_e32 v96, 1.0, v165
	v_pk_add_f32 v[168:169], v[102:103], 1.0 op_sel_hi:[1,0] neg_lo:[1,0] neg_hi:[1,0]
	v_rcp_f32_e32 v167, v96
	v_fma_f32 v96, v166, v168, v102
	v_pk_add_f32 v[170:171], v[104:105], 1.0 op_sel_hi:[1,0] neg_lo:[1,0] neg_hi:[1,0]
	v_pk_mul_f32 v[164:165], v[164:165], v[166:167]
	v_log_f32_e32 v96, v96
	v_pk_mul_f32 v[164:165], v[164:165], v[168:169]
	v_pk_add_f32 v[174:175], v[100:101], 1.0 op_sel_hi:[1,0] neg_lo:[1,0] neg_hi:[1,0]
	v_mul_f32_e32 v102, 0x3f317217, v96
	v_fma_f32 v102, v96, s1, -v102
	v_fmac_f32_e32 v102, 0x3377d1cf, v96
	v_fmac_f32_e32 v102, 0x3f317217, v96
	v_cmp_lt_f32_e64 s[14:15], |v96|, s4
	s_nop 1
	v_cndmask_b32_e64 v96, v96, v102, s[14:15]
	v_mov_b32_e32 v102, v96
	v_fma_f32 v96, v167, v169, v103
	v_log_f32_e32 v96, v96
	s_nop 0
	v_mul_f32_e32 v103, 0x3f317217, v96
	v_fma_f32 v103, v96, s1, -v103
	v_fmac_f32_e32 v103, 0x3377d1cf, v96
	v_fmac_f32_e32 v103, 0x3f317217, v96
	v_cmp_lt_f32_e64 s[14:15], |v96|, s4
	s_nop 1
	v_cndmask_b32_e64 v96, v96, v103, s[14:15]
	v_mov_b32_e32 v103, v96
	v_med3_f32 v96, v108, s17, v231
	v_mul_f32_e32 v96, 0xbfb8aa3b, v96
	v_exp_f32_e32 v166, v96
	s_nop 0
	v_add_f32_e32 v96, 1.0, v166
	v_rcp_f32_e32 v168, v96
	v_med3_f32 v96, v109, s17, v231
	v_mul_f32_e32 v96, 0xbfb8aa3b, v96
	v_exp_f32_e32 v167, v96
	s_nop 0
	v_add_f32_e32 v96, 1.0, v167
	v_rcp_f32_e32 v169, v96
	v_fma_f32 v96, v168, v170, v104
	v_fmac_f32_e32 v105, v169, v171
	v_log_f32_e32 v96, v96
	v_pk_mul_f32 v[166:167], v[166:167], v[168:169]
	v_mul_f32_e32 v104, 0x3f317217, v96
	v_fma_f32 v104, v96, s1, -v104
	v_fmac_f32_e32 v104, 0x3377d1cf, v96
	v_fmac_f32_e32 v104, 0x3f317217, v96
	v_cmp_lt_f32_e64 s[14:15], |v96|, s4
	v_pk_mul_f32 v[166:167], v[166:167], v[170:171]
	s_nop 0
	v_cndmask_b32_e64 v96, v96, v104, s[14:15]
	v_mov_b32_e32 v104, v96
	v_mov_b32_e32 v96, v105
	v_log_f32_e32 v96, v96
	s_nop 0
	v_mul_f32_e32 v105, 0x3f317217, v96
	v_fma_f32 v105, v96, s1, -v105
	v_fmac_f32_e32 v105, 0x3377d1cf, v96
	v_fmac_f32_e32 v105, 0x3f317217, v96
	v_cmp_lt_f32_e64 s[14:15], |v96|, s4
	s_nop 1
	v_cndmask_b32_e64 v96, v96, v105, s[14:15]
	v_mov_b32_e32 v105, v96
	v_med3_f32 v96, v154, s17, v231
	v_mul_f32_e32 v96, 0xbfb8aa3b, v96
	v_exp_f32_e32 v170, v96
	s_nop 0
	v_add_f32_e32 v96, 1.0, v170
	v_rcp_f32_e32 v168, v96
	v_med3_f32 v96, v155, s17, v231
	v_mul_f32_e32 v96, 0xbfb8aa3b, v96
	v_exp_f32_e32 v171, v96
	s_nop 0
	v_add_f32_e32 v96, 1.0, v171
	v_rcp_f32_e32 v169, v96
	v_fma_f32 v96, v168, v172, v98
	v_pk_mul_f32 v[170:171], v[170:171], v[168:169]
	v_log_f32_e32 v96, v96
	v_pk_mul_f32 v[170:171], v[170:171], v[172:173]
	v_mul_f32_e32 v98, 0x3f317217, v96
	v_fma_f32 v98, v96, s1, -v98
	v_fmac_f32_e32 v98, 0x3377d1cf, v96
	v_fmac_f32_e32 v98, 0x3f317217, v96
	v_cmp_lt_f32_e64 s[14:15], |v96|, s4
	s_nop 1
	v_cndmask_b32_e64 v96, v96, v98, s[14:15]
	v_mov_b32_e32 v98, v96
	v_fma_f32 v96, v169, v173, v99
	v_log_f32_e32 v96, v96
	s_nop 0
	v_mul_f32_e32 v99, 0x3f317217, v96
	v_fma_f32 v99, v96, s1, -v99
	v_fmac_f32_e32 v99, 0x3377d1cf, v96
	v_fmac_f32_e32 v99, 0x3f317217, v96
	v_cmp_lt_f32_e64 s[14:15], |v96|, s4
	s_nop 1
	v_cndmask_b32_e64 v96, v96, v99, s[14:15]
	v_mov_b32_e32 v99, v96
	v_med3_f32 v96, v156, s17, v231
	v_mul_f32_e32 v96, 0xbfb8aa3b, v96
	v_exp_f32_e32 v168, v96
	s_nop 0
	v_add_f32_e32 v96, 1.0, v168
	v_rcp_f32_e32 v172, v96
	v_med3_f32 v96, v157, s17, v231
	v_mul_f32_e32 v96, 0xbfb8aa3b, v96
	v_exp_f32_e32 v169, v96
	s_nop 0
	v_add_f32_e32 v96, 1.0, v169
	v_rcp_f32_e32 v173, v96
	v_fma_f32 v96, v172, v174, v100
	v_fmac_f32_e32 v101, v173, v175
	v_log_f32_e32 v96, v96
	v_pk_mul_f32 v[168:169], v[168:169], v[172:173]
	v_mul_f32_e32 v100, 0x3f317217, v96
	v_fma_f32 v100, v96, s1, -v100
	v_fmac_f32_e32 v100, 0x3377d1cf, v96
	v_fmac_f32_e32 v100, 0x3f317217, v96
	v_cmp_lt_f32_e64 s[14:15], |v96|, s4
	v_pk_mul_f32 v[168:169], v[168:169], v[174:175]
	s_nop 0
	v_cndmask_b32_e64 v96, v96, v100, s[14:15]
	v_mov_b32_e32 v100, v96
	v_mov_b32_e32 v96, v101
	v_log_f32_e32 v96, v96
	s_nop 0
	v_mul_f32_e32 v101, 0x3f317217, v96
	v_fma_f32 v101, v96, s1, -v101
	v_fmac_f32_e32 v101, 0x3377d1cf, v96
	v_fmac_f32_e32 v101, 0x3f317217, v96
	v_cmp_lt_f32_e64 s[14:15], |v96|, s4
	s_nop 1
	v_cndmask_b32_e64 v96, v96, v101, s[14:15]
	v_mov_b32_e32 v101, v96
	global_store_dwordx4 v[120:121], v[102:105], off
	global_store_dwordx4 v[120:121], v[98:101], off offset:16
	s_nop 0
	v_lshl_add_u64 v[102:103], v[158:159], 1, v[118:119]
	v_cvt_pk_bf16_f32 v98, v164, v165
	v_cvt_pk_bf16_f32 v99, v166, v167
	v_cvt_pk_bf16_f32 v100, v170, v171
	v_cvt_pk_bf16_f32 v101, v168, v169
	global_store_dwordx4 v[102:103], v[98:101], off
	s_mov_b64 s[14:15], 0
	s_branch .LBB0_670

.LBB0_686:
	s_andn2_b64 vcc, exec, s[14:15]
	s_cbranch_vccnz .LBB0_688
	v_lshl_add_u32 v106, s93, 8, v194
	v_ashrrev_i32_e32 v107, 31, v106
	v_lshlrev_b64 v[108:109], 2, v[106:107]
	v_lshl_add_u64 v[92:93], s[80:81], 0, v[108:109]
	global_load_dwordx4 v[88:91], v[92:93], off offset:16
	s_nop 0
	global_load_dwordx4 v[92:95], v[92:93], off
	s_mov_b32 s17, 0xc2700000
	v_med3_f32 v96, v110, s17, v231
	v_mul_f32_e32 v96, 0xbfb8aa3b, v96
	v_exp_f32_e32 v116, v96
	s_mov_b32 s1, 0x3f317217
	v_lshl_add_u64 v[108:109], v[104:105], 0, v[108:109]
	v_add_f32_e32 v96, 1.0, v116
	v_rcp_f32_e32 v152, v96
	v_med3_f32 v96, v111, s17, v231
	v_mul_f32_e32 v96, 0xbfb8aa3b, v96
	v_exp_f32_e32 v117, v96
	s_waitcnt vmcnt(0)
	v_pk_add_f32 v[158:159], v[88:89], 1.0 op_sel_hi:[1,0] neg_lo:[1,0] neg_hi:[1,0]
	v_pk_add_f32 v[154:155], v[92:93], 1.0 op_sel_hi:[1,0] neg_lo:[1,0] neg_hi:[1,0]
	v_add_f32_e32 v96, 1.0, v117
	v_fma_f32 v92, v152, v154, v92
	v_rcp_f32_e32 v153, v96
	v_pk_add_f32 v[156:157], v[94:95], 1.0 op_sel_hi:[1,0] neg_lo:[1,0] neg_hi:[1,0]
	v_log_f32_e32 v92, v92
	v_fma_f32 v93, v153, v155, v93
	v_pk_mul_f32 v[116:117], v[116:117], v[152:153]
	v_pk_add_f32 v[160:161], v[90:91], 1.0 op_sel_hi:[1,0] neg_lo:[1,0] neg_hi:[1,0]
	v_mul_f32_e32 v96, 0x3f317217, v92
	v_fma_f32 v96, v92, s1, -v96
	v_fmac_f32_e32 v96, 0x3377d1cf, v92
	v_fmac_f32_e32 v96, 0x3f317217, v92
	v_cmp_lt_f32_e64 s[14:15], |v92|, s4
	v_pk_mul_f32 v[116:117], v[116:117], v[154:155]
	s_nop 0
	v_cndmask_b32_e64 v92, v92, v96, s[14:15]
	v_log_f32_e32 v93, v93
	s_nop 0
	v_mul_f32_e32 v96, 0x3f317217, v93
	v_fma_f32 v96, v93, s1, -v96
	v_fmac_f32_e32 v96, 0x3377d1cf, v93
	v_fmac_f32_e32 v96, 0x3f317217, v93
	v_cmp_lt_f32_e64 s[14:15], |v93|, s4
	s_nop 1
	v_cndmask_b32_e64 v93, v93, v96, s[14:15]
	v_med3_f32 v96, v118, s17, v231
	v_mul_f32_e32 v96, 0xbfb8aa3b, v96
	v_exp_f32_e32 v152, v96
	s_nop 0
	v_add_f32_e32 v96, 1.0, v152
	v_rcp_f32_e32 v154, v96
	v_med3_f32 v96, v119, s17, v231
	v_mul_f32_e32 v96, 0xbfb8aa3b, v96
	v_exp_f32_e32 v153, v96
	v_fma_f32 v94, v154, v156, v94
	v_add_f32_e32 v96, 1.0, v153
	v_rcp_f32_e32 v155, v96
	v_log_f32_e32 v94, v94
	v_fmac_f32_e32 v95, v155, v157
	v_pk_mul_f32 v[152:153], v[152:153], v[154:155]
	v_mul_f32_e32 v96, 0x3f317217, v94
	v_fma_f32 v96, v94, s1, -v96
	v_fmac_f32_e32 v96, 0x3377d1cf, v94
	v_fmac_f32_e32 v96, 0x3f317217, v94
	v_cmp_lt_f32_e64 s[14:15], |v94|, s4
	v_pk_mul_f32 v[152:153], v[152:153], v[156:157]
	s_nop 0
	v_cndmask_b32_e64 v94, v94, v96, s[14:15]
	v_log_f32_e32 v95, v95
	s_nop 0
	v_mul_f32_e32 v96, 0x3f317217, v95
	v_fma_f32 v96, v95, s1, -v96
	v_fmac_f32_e32 v96, 0x3377d1cf, v95
	v_fmac_f32_e32 v96, 0x3f317217, v95
	v_cmp_lt_f32_e64 s[14:15], |v95|, s4
	s_nop 1
	v_cndmask_b32_e64 v95, v95, v96, s[14:15]
	v_med3_f32 v96, v120, s17, v231
	v_mul_f32_e32 v96, 0xbfb8aa3b, v96
	v_exp_f32_e32 v156, v96
	s_nop 0
	v_add_f32_e32 v96, 1.0, v156
	v_rcp_f32_e32 v154, v96
	v_med3_f32 v96, v121, s17, v231
	v_mul_f32_e32 v96, 0xbfb8aa3b, v96
	v_exp_f32_e32 v157, v96
	v_fma_f32 v88, v154, v158, v88
	v_add_f32_e32 v96, 1.0, v157
	v_rcp_f32_e32 v155, v96
	v_log_f32_e32 v88, v88
	v_fma_f32 v89, v155, v159, v89
	v_pk_mul_f32 v[156:157], v[156:157], v[154:155]
	v_mul_f32_e32 v96, 0x3f317217, v88
	v_fma_f32 v96, v88, s1, -v96
	v_fmac_f32_e32 v96, 0x3377d1cf, v88
	v_fmac_f32_e32 v96, 0x3f317217, v88
	v_cmp_lt_f32_e64 s[14:15], |v88|, s4
	v_pk_mul_f32 v[156:157], v[156:157], v[158:159]
	s_nop 0
	v_cndmask_b32_e64 v88, v88, v96, s[14:15]
	v_log_f32_e32 v89, v89
	s_nop 0
	v_mul_f32_e32 v96, 0x3f317217, v89
	v_fma_f32 v96, v89, s1, -v96
	v_fmac_f32_e32 v96, 0x3377d1cf, v89
	v_fmac_f32_e32 v96, 0x3f317217, v89
	v_cmp_lt_f32_e64 s[14:15], |v89|, s4
	s_nop 1
	v_cndmask_b32_e64 v89, v89, v96, s[14:15]
	v_med3_f32 v96, v150, s17, v231
	v_mul_f32_e32 v96, 0xbfb8aa3b, v96
	v_exp_f32_e32 v154, v96
	s_nop 0
	v_add_f32_e32 v96, 1.0, v154
	v_rcp_f32_e32 v158, v96
	v_med3_f32 v96, v151, s17, v231
	v_mul_f32_e32 v96, 0xbfb8aa3b, v96
	v_exp_f32_e32 v155, v96
	v_fma_f32 v90, v158, v160, v90
	v_add_f32_e32 v96, 1.0, v155
	v_rcp_f32_e32 v159, v96
	v_log_f32_e32 v90, v90
	v_fmac_f32_e32 v91, v159, v161
	v_pk_mul_f32 v[154:155], v[154:155], v[158:159]
	v_mul_f32_e32 v96, 0x3f317217, v90
	v_fma_f32 v96, v90, s1, -v96
	v_fmac_f32_e32 v96, 0x3377d1cf, v90
	v_fmac_f32_e32 v96, 0x3f317217, v90
	v_cmp_lt_f32_e64 s[14:15], |v90|, s4
	v_pk_mul_f32 v[154:155], v[154:155], v[160:161]
	s_nop 0
	v_cndmask_b32_e64 v90, v90, v96, s[14:15]
	v_log_f32_e32 v91, v91
	s_nop 0
	v_mul_f32_e32 v96, 0x3f317217, v91
	v_fma_f32 v96, v91, s1, -v96
	v_fmac_f32_e32 v96, 0x3377d1cf, v91
	v_fmac_f32_e32 v96, 0x3f317217, v91
	v_cmp_lt_f32_e64 s[14:15], |v91|, s4
	s_nop 1
	v_cndmask_b32_e64 v91, v91, v96, s[14:15]
	global_store_dwordx4 v[108:109], v[92:95], off
	global_store_dwordx4 v[108:109], v[88:91], off offset:16
	s_nop 0
	v_lshl_add_u64 v[92:93], v[106:107], 1, v[102:103]
	v_cvt_pk_bf16_f32 v88, v116, v117
	v_cvt_pk_bf16_f32 v89, v152, v153
	v_cvt_pk_bf16_f32 v90, v156, v157
	v_cvt_pk_bf16_f32 v91, v154, v155
	global_store_dwordx4 v[92:93], v[88:91], off

.LBB0_718:
	s_andn2_b64 vcc, exec, s[14:15]
	s_cbranch_vccnz .LBB0_720
	v_lshl_add_u32 v114, s95, 7, v194
	v_ashrrev_i32_e32 v115, 31, v114
	v_lshlrev_b64 v[118:119], 2, v[114:115]
	v_lshl_add_u64 v[84:85], s[80:81], 0, v[118:119]
	global_load_dwordx4 v[80:83], v[84:85], off offset:16
	s_nop 0
	global_load_dwordx4 v[84:87], v[84:85], off
	s_mov_b32 s17, 0xc2700000
	v_med3_f32 v96, v88, s17, v231
	v_mul_f32_e32 v96, 0xbfb8aa3b, v96
	v_exp_f32_e32 v120, v96
	s_mov_b32 s1, 0x3f317217
	v_lshl_add_u64 v[104:105], v[104:105], 0, v[118:119]
	v_add_f32_e32 v96, 1.0, v120
	v_rcp_f32_e32 v150, v96
	v_med3_f32 v96, v89, s17, v231
	v_mul_f32_e32 v96, 0xbfb8aa3b, v96
	v_exp_f32_e32 v121, v96
	s_waitcnt vmcnt(0)
	v_pk_add_f32 v[156:157], v[80:81], 1.0 op_sel_hi:[1,0] neg_lo:[1,0] neg_hi:[1,0]
	v_pk_add_f32 v[152:153], v[84:85], 1.0 op_sel_hi:[1,0] neg_lo:[1,0] neg_hi:[1,0]
	v_add_f32_e32 v96, 1.0, v121
	v_fma_f32 v84, v150, v152, v84
	v_rcp_f32_e32 v151, v96
	v_pk_add_f32 v[154:155], v[86:87], 1.0 op_sel_hi:[1,0] neg_lo:[1,0] neg_hi:[1,0]
	v_log_f32_e32 v84, v84
	v_fma_f32 v85, v151, v153, v85
	v_pk_mul_f32 v[120:121], v[120:121], v[150:151]
	v_pk_add_f32 v[158:159], v[82:83], 1.0 op_sel_hi:[1,0] neg_lo:[1,0] neg_hi:[1,0]
	v_mul_f32_e32 v96, 0x3f317217, v84
	v_fma_f32 v96, v84, s1, -v96
	v_fmac_f32_e32 v96, 0x3377d1cf, v84
	v_fmac_f32_e32 v96, 0x3f317217, v84
	v_cmp_lt_f32_e64 s[14:15], |v84|, s4
	v_pk_mul_f32 v[120:121], v[120:121], v[152:153]
	s_nop 0
	v_cndmask_b32_e64 v84, v84, v96, s[14:15]
	v_log_f32_e32 v85, v85
	s_nop 0
	v_mul_f32_e32 v96, 0x3f317217, v85
	v_fma_f32 v96, v85, s1, -v96
	v_fmac_f32_e32 v96, 0x3377d1cf, v85
	v_fmac_f32_e32 v96, 0x3f317217, v85
	v_cmp_lt_f32_e64 s[14:15], |v85|, s4
	s_nop 1
	v_cndmask_b32_e64 v85, v85, v96, s[14:15]
	v_med3_f32 v96, v90, s17, v231
	v_mul_f32_e32 v96, 0xbfb8aa3b, v96
	v_exp_f32_e32 v150, v96
	s_nop 0
	v_add_f32_e32 v96, 1.0, v150
	v_rcp_f32_e32 v152, v96
	v_med3_f32 v96, v91, s17, v231
	v_mul_f32_e32 v96, 0xbfb8aa3b, v96
	v_exp_f32_e32 v151, v96
	v_fma_f32 v86, v152, v154, v86
	v_add_f32_e32 v96, 1.0, v151
	v_rcp_f32_e32 v153, v96
	v_log_f32_e32 v86, v86
	v_fmac_f32_e32 v87, v153, v155
	v_pk_mul_f32 v[150:151], v[150:151], v[152:153]
	v_mul_f32_e32 v96, 0x3f317217, v86
	v_fma_f32 v96, v86, s1, -v96
	v_fmac_f32_e32 v96, 0x3377d1cf, v86
	v_fmac_f32_e32 v96, 0x3f317217, v86
	v_cmp_lt_f32_e64 s[14:15], |v86|, s4
	v_pk_mul_f32 v[150:151], v[150:151], v[154:155]
	s_nop 0
	v_cndmask_b32_e64 v86, v86, v96, s[14:15]
	v_log_f32_e32 v87, v87
	s_nop 0
	v_mul_f32_e32 v96, 0x3f317217, v87
	v_fma_f32 v96, v87, s1, -v96
	v_fmac_f32_e32 v96, 0x3377d1cf, v87
	v_fmac_f32_e32 v96, 0x3f317217, v87
	v_cmp_lt_f32_e64 s[14:15], |v87|, s4
	s_nop 1
	v_cndmask_b32_e64 v87, v87, v96, s[14:15]
	v_med3_f32 v96, v110, s17, v231
	v_mul_f32_e32 v96, 0xbfb8aa3b, v96
	v_exp_f32_e32 v154, v96
	s_nop 0
	v_add_f32_e32 v96, 1.0, v154
	v_rcp_f32_e32 v152, v96
	v_med3_f32 v96, v111, s17, v231
	v_mul_f32_e32 v96, 0xbfb8aa3b, v96
	v_exp_f32_e32 v155, v96
	v_fma_f32 v80, v152, v156, v80
	v_add_f32_e32 v96, 1.0, v155
	v_rcp_f32_e32 v153, v96
	v_log_f32_e32 v80, v80
	v_fma_f32 v81, v153, v157, v81
	v_pk_mul_f32 v[154:155], v[154:155], v[152:153]
	v_mul_f32_e32 v96, 0x3f317217, v80
	v_fma_f32 v96, v80, s1, -v96
	v_fmac_f32_e32 v96, 0x3377d1cf, v80
	v_fmac_f32_e32 v96, 0x3f317217, v80
	v_cmp_lt_f32_e64 s[14:15], |v80|, s4
	v_pk_mul_f32 v[154:155], v[154:155], v[156:157]
	s_nop 0
	v_cndmask_b32_e64 v80, v80, v96, s[14:15]
	v_log_f32_e32 v81, v81
	s_nop 0
	v_mul_f32_e32 v96, 0x3f317217, v81
	v_fma_f32 v96, v81, s1, -v96
	v_fmac_f32_e32 v96, 0x3377d1cf, v81
	v_fmac_f32_e32 v96, 0x3f317217, v81
	v_cmp_lt_f32_e64 s[14:15], |v81|, s4
	s_nop 1
	v_cndmask_b32_e64 v81, v81, v96, s[14:15]
	v_med3_f32 v96, v112, s17, v231
	v_mul_f32_e32 v96, 0xbfb8aa3b, v96
	v_exp_f32_e32 v152, v96
	s_nop 0
	v_add_f32_e32 v96, 1.0, v152
	v_rcp_f32_e32 v156, v96
	v_med3_f32 v96, v113, s17, v231
	v_mul_f32_e32 v96, 0xbfb8aa3b, v96
	v_exp_f32_e32 v153, v96
	v_fma_f32 v82, v156, v158, v82
	v_add_f32_e32 v96, 1.0, v153
	v_rcp_f32_e32 v157, v96
	v_log_f32_e32 v82, v82
	v_fmac_f32_e32 v83, v157, v159
	v_pk_mul_f32 v[152:153], v[152:153], v[156:157]
	v_mul_f32_e32 v96, 0x3f317217, v82
	v_fma_f32 v96, v82, s1, -v96
	v_fmac_f32_e32 v96, 0x3377d1cf, v82
	v_fmac_f32_e32 v96, 0x3f317217, v82
	v_cmp_lt_f32_e64 s[14:15], |v82|, s4
	v_pk_mul_f32 v[152:153], v[152:153], v[158:159]
	s_nop 0
	v_cndmask_b32_e64 v82, v82, v96, s[14:15]
	v_log_f32_e32 v83, v83
	s_nop 0
	v_mul_f32_e32 v96, 0x3f317217, v83
	v_fma_f32 v96, v83, s1, -v96
	v_fmac_f32_e32 v96, 0x3377d1cf, v83
	v_fmac_f32_e32 v96, 0x3f317217, v83
	v_cmp_lt_f32_e64 s[14:15], |v83|, s4
	s_nop 1
	v_cndmask_b32_e64 v83, v83, v96, s[14:15]
	global_store_dwordx4 v[104:105], v[84:87], off
	global_store_dwordx4 v[104:105], v[80:83], off offset:16
	s_nop 0
	v_lshl_add_u64 v[84:85], v[114:115], 1, v[102:103]
	v_cvt_pk_bf16_f32 v80, v120, v121
	v_cvt_pk_bf16_f32 v81, v150, v151
	v_cvt_pk_bf16_f32 v82, v154, v155
	v_cvt_pk_bf16_f32 v83, v152, v153
	global_store_dwordx4 v[84:85], v[80:83], off
	s_mov_b64 s[14:15], 0
	s_branch .LBB0_737

.LBB0_753:
	s_andn2_b64 vcc, exec, s[14:15]
	s_cbranch_vccnz .LBB0_755
	v_lshl_add_u32 v88, s93, 8, v194
	v_ashrrev_i32_e32 v89, 31, v88
	v_lshlrev_b64 v[90:91], 2, v[88:89]
	v_lshl_add_u64 v[76:77], s[80:81], 0, v[90:91]
	global_load_dwordx4 v[72:75], v[76:77], off offset:16
	s_nop 0
	global_load_dwordx4 v[76:79], v[76:77], off
	s_mov_b32 s17, 0xc2700000
	v_med3_f32 v95, v92, s17, v231
	v_mul_f32_e32 v95, 0xbfb8aa3b, v95
	v_exp_f32_e32 v100, v95
	s_mov_b32 s1, 0x3f317217
	v_lshl_add_u64 v[90:91], v[86:87], 0, v[90:91]
	v_add_f32_e32 v95, 1.0, v100
	v_rcp_f32_e32 v108, v95
	v_med3_f32 v95, v93, s17, v231
	v_mul_f32_e32 v95, 0xbfb8aa3b, v95
	v_exp_f32_e32 v101, v95
	s_waitcnt vmcnt(0)
	v_pk_add_f32 v[114:115], v[72:73], 1.0 op_sel_hi:[1,0] neg_lo:[1,0] neg_hi:[1,0]
	v_pk_add_f32 v[110:111], v[76:77], 1.0 op_sel_hi:[1,0] neg_lo:[1,0] neg_hi:[1,0]
	v_add_f32_e32 v95, 1.0, v101
	v_fma_f32 v76, v108, v110, v76
	v_rcp_f32_e32 v109, v95
	v_pk_add_f32 v[112:113], v[78:79], 1.0 op_sel_hi:[1,0] neg_lo:[1,0] neg_hi:[1,0]
	v_log_f32_e32 v76, v76
	v_fma_f32 v77, v109, v111, v77
	v_pk_mul_f32 v[100:101], v[100:101], v[108:109]
	v_pk_add_f32 v[116:117], v[74:75], 1.0 op_sel_hi:[1,0] neg_lo:[1,0] neg_hi:[1,0]
	v_mul_f32_e32 v95, 0x3f317217, v76
	v_fma_f32 v95, v76, s1, -v95
	v_fmac_f32_e32 v95, 0x3377d1cf, v76
	v_fmac_f32_e32 v95, 0x3f317217, v76
	v_cmp_lt_f32_e64 s[14:15], |v76|, s4
	v_pk_mul_f32 v[100:101], v[100:101], v[110:111]
	s_nop 0
	v_cndmask_b32_e64 v76, v76, v95, s[14:15]
	v_log_f32_e32 v77, v77
	s_nop 0
	v_mul_f32_e32 v95, 0x3f317217, v77
	v_fma_f32 v95, v77, s1, -v95
	v_fmac_f32_e32 v95, 0x3377d1cf, v77
	v_fmac_f32_e32 v95, 0x3f317217, v77
	v_cmp_lt_f32_e64 s[14:15], |v77|, s4
	s_nop 1
	v_cndmask_b32_e64 v77, v77, v95, s[14:15]
	v_med3_f32 v95, v102, s17, v231
	v_mul_f32_e32 v95, 0xbfb8aa3b, v95
	v_exp_f32_e32 v108, v95
	s_nop 0
	v_add_f32_e32 v95, 1.0, v108
	v_rcp_f32_e32 v110, v95
	v_med3_f32 v95, v103, s17, v231
	v_mul_f32_e32 v95, 0xbfb8aa3b, v95
	v_exp_f32_e32 v109, v95
	v_fma_f32 v78, v110, v112, v78
	v_add_f32_e32 v95, 1.0, v109
	v_rcp_f32_e32 v111, v95
	v_log_f32_e32 v78, v78
	v_fmac_f32_e32 v79, v111, v113
	v_pk_mul_f32 v[108:109], v[108:109], v[110:111]
	v_mul_f32_e32 v95, 0x3f317217, v78
	v_fma_f32 v95, v78, s1, -v95
	v_fmac_f32_e32 v95, 0x3377d1cf, v78
	v_fmac_f32_e32 v95, 0x3f317217, v78
	v_cmp_lt_f32_e64 s[14:15], |v78|, s4
	v_pk_mul_f32 v[108:109], v[108:109], v[112:113]
	s_nop 0
	v_cndmask_b32_e64 v78, v78, v95, s[14:15]
	v_log_f32_e32 v79, v79
	s_nop 0
	v_mul_f32_e32 v95, 0x3f317217, v79
	v_fma_f32 v95, v79, s1, -v95
	v_fmac_f32_e32 v95, 0x3377d1cf, v79
	v_fmac_f32_e32 v95, 0x3f317217, v79
	v_cmp_lt_f32_e64 s[14:15], |v79|, s4
	s_nop 1
	v_cndmask_b32_e64 v79, v79, v95, s[14:15]
	v_med3_f32 v95, v104, s17, v231
	v_mul_f32_e32 v95, 0xbfb8aa3b, v95
	v_exp_f32_e32 v112, v95
	s_nop 0
	v_add_f32_e32 v95, 1.0, v112
	v_rcp_f32_e32 v110, v95
	v_med3_f32 v95, v105, s17, v231
	v_mul_f32_e32 v95, 0xbfb8aa3b, v95
	v_exp_f32_e32 v113, v95
	v_fma_f32 v72, v110, v114, v72
	v_add_f32_e32 v95, 1.0, v113
	v_rcp_f32_e32 v111, v95
	v_log_f32_e32 v72, v72
	v_fma_f32 v73, v111, v115, v73
	v_pk_mul_f32 v[112:113], v[112:113], v[110:111]
	v_mul_f32_e32 v95, 0x3f317217, v72
	v_fma_f32 v95, v72, s1, -v95
	v_fmac_f32_e32 v95, 0x3377d1cf, v72
	v_fmac_f32_e32 v95, 0x3f317217, v72
	v_cmp_lt_f32_e64 s[14:15], |v72|, s4
	v_pk_mul_f32 v[112:113], v[112:113], v[114:115]
	s_nop 0
	v_cndmask_b32_e64 v72, v72, v95, s[14:15]
	v_log_f32_e32 v73, v73
	s_nop 0
	v_mul_f32_e32 v95, 0x3f317217, v73
	v_fma_f32 v95, v73, s1, -v95
	v_fmac_f32_e32 v95, 0x3377d1cf, v73
	v_fmac_f32_e32 v95, 0x3f317217, v73
	v_cmp_lt_f32_e64 s[14:15], |v73|, s4
	s_nop 1
	v_cndmask_b32_e64 v73, v73, v95, s[14:15]
	v_med3_f32 v95, v106, s17, v231
	v_mul_f32_e32 v95, 0xbfb8aa3b, v95
	v_exp_f32_e32 v110, v95
	s_nop 0
	v_add_f32_e32 v95, 1.0, v110
	v_rcp_f32_e32 v114, v95
	v_med3_f32 v95, v107, s17, v231
	v_mul_f32_e32 v95, 0xbfb8aa3b, v95
	v_exp_f32_e32 v111, v95
	v_fma_f32 v74, v114, v116, v74
	v_add_f32_e32 v95, 1.0, v111
	v_rcp_f32_e32 v115, v95
	v_log_f32_e32 v74, v74
	v_fmac_f32_e32 v75, v115, v117
	v_pk_mul_f32 v[110:111], v[110:111], v[114:115]
	v_mul_f32_e32 v95, 0x3f317217, v74
	v_fma_f32 v95, v74, s1, -v95
	v_fmac_f32_e32 v95, 0x3377d1cf, v74
	v_fmac_f32_e32 v95, 0x3f317217, v74
	v_cmp_lt_f32_e64 s[14:15], |v74|, s4
	v_pk_mul_f32 v[110:111], v[110:111], v[116:117]
	s_nop 0
	v_cndmask_b32_e64 v74, v74, v95, s[14:15]
	v_log_f32_e32 v75, v75
	s_nop 0
	v_mul_f32_e32 v95, 0x3f317217, v75
	v_fma_f32 v95, v75, s1, -v95
	v_fmac_f32_e32 v95, 0x3377d1cf, v75
	v_fmac_f32_e32 v95, 0x3f317217, v75
	v_cmp_lt_f32_e64 s[14:15], |v75|, s4
	s_nop 1
	v_cndmask_b32_e64 v75, v75, v95, s[14:15]
	global_store_dwordx4 v[90:91], v[76:79], off
	global_store_dwordx4 v[90:91], v[72:75], off offset:16
	s_nop 0
	v_lshl_add_u64 v[76:77], v[88:89], 1, v[84:85]
	v_cvt_pk_bf16_f32 v72, v100, v101
	v_cvt_pk_bf16_f32 v73, v108, v109
	v_cvt_pk_bf16_f32 v74, v112, v113
	v_cvt_pk_bf16_f32 v75, v110, v111
	global_store_dwordx4 v[76:77], v[72:75], off

.LBB0_785:
	s_andn2_b64 vcc, exec, s[14:15]
	s_cbranch_vccnz .LBB0_787
	v_lshl_add_u32 v98, s95, 7, v194
	v_ashrrev_i32_e32 v99, 31, v98
	v_lshlrev_b64 v[102:103], 2, v[98:99]
	v_lshl_add_u64 v[68:69], s[80:81], 0, v[102:103]
	global_load_dwordx4 v[64:67], v[68:69], off offset:16
	s_nop 0
	global_load_dwordx4 v[68:71], v[68:69], off
	s_mov_b32 s17, 0xc2700000
	v_med3_f32 v81, v72, s17, v231
	v_mul_f32_e32 v81, 0xbfb8aa3b, v81
	v_exp_f32_e32 v104, v81
	s_mov_b32 s1, 0x3f317217
	v_lshl_add_u64 v[86:87], v[86:87], 0, v[102:103]
	v_add_f32_e32 v81, 1.0, v104
	v_rcp_f32_e32 v106, v81
	v_med3_f32 v81, v73, s17, v231
	v_mul_f32_e32 v81, 0xbfb8aa3b, v81
	v_exp_f32_e32 v105, v81
	s_waitcnt vmcnt(0)
	v_pk_add_f32 v[112:113], v[64:65], 1.0 op_sel_hi:[1,0] neg_lo:[1,0] neg_hi:[1,0]
	v_pk_add_f32 v[108:109], v[68:69], 1.0 op_sel_hi:[1,0] neg_lo:[1,0] neg_hi:[1,0]
	v_add_f32_e32 v81, 1.0, v105
	v_fma_f32 v68, v106, v108, v68
	v_rcp_f32_e32 v107, v81
	v_pk_add_f32 v[110:111], v[70:71], 1.0 op_sel_hi:[1,0] neg_lo:[1,0] neg_hi:[1,0]
	v_log_f32_e32 v68, v68
	v_fma_f32 v69, v107, v109, v69
	v_pk_mul_f32 v[104:105], v[104:105], v[106:107]
	v_pk_add_f32 v[114:115], v[66:67], 1.0 op_sel_hi:[1,0] neg_lo:[1,0] neg_hi:[1,0]
	v_mul_f32_e32 v81, 0x3f317217, v68
	v_fma_f32 v81, v68, s1, -v81
	v_fmac_f32_e32 v81, 0x3377d1cf, v68
	v_fmac_f32_e32 v81, 0x3f317217, v68
	v_cmp_lt_f32_e64 s[14:15], |v68|, s4
	v_pk_mul_f32 v[104:105], v[104:105], v[108:109]
	s_nop 0
	v_cndmask_b32_e64 v68, v68, v81, s[14:15]
	v_log_f32_e32 v69, v69
	s_nop 0
	v_mul_f32_e32 v81, 0x3f317217, v69
	v_fma_f32 v81, v69, s1, -v81
	v_fmac_f32_e32 v81, 0x3377d1cf, v69
	v_fmac_f32_e32 v81, 0x3f317217, v69
	v_cmp_lt_f32_e64 s[14:15], |v69|, s4
	s_nop 1
	v_cndmask_b32_e64 v69, v69, v81, s[14:15]
	v_med3_f32 v81, v74, s17, v231
	v_mul_f32_e32 v81, 0xbfb8aa3b, v81
	v_exp_f32_e32 v106, v81
	s_nop 0
	v_add_f32_e32 v81, 1.0, v106
	v_rcp_f32_e32 v108, v81
	v_med3_f32 v81, v75, s17, v231
	v_mul_f32_e32 v81, 0xbfb8aa3b, v81
	v_exp_f32_e32 v107, v81
	v_fma_f32 v70, v108, v110, v70
	v_add_f32_e32 v81, 1.0, v107
	v_rcp_f32_e32 v109, v81
	v_log_f32_e32 v70, v70
	v_fmac_f32_e32 v71, v109, v111
	v_pk_mul_f32 v[106:107], v[106:107], v[108:109]
	v_mul_f32_e32 v81, 0x3f317217, v70
	v_fma_f32 v81, v70, s1, -v81
	v_fmac_f32_e32 v81, 0x3377d1cf, v70
	v_fmac_f32_e32 v81, 0x3f317217, v70
	v_cmp_lt_f32_e64 s[14:15], |v70|, s4
	v_pk_mul_f32 v[106:107], v[106:107], v[110:111]
	s_nop 0
	v_cndmask_b32_e64 v70, v70, v81, s[14:15]
	v_log_f32_e32 v71, v71
	s_nop 0
	v_mul_f32_e32 v81, 0x3f317217, v71
	v_fma_f32 v81, v71, s1, -v81
	v_fmac_f32_e32 v81, 0x3377d1cf, v71
	v_fmac_f32_e32 v81, 0x3f317217, v71
	v_cmp_lt_f32_e64 s[14:15], |v71|, s4
	s_nop 1
	v_cndmask_b32_e64 v71, v71, v81, s[14:15]
	v_med3_f32 v81, v92, s17, v231
	v_mul_f32_e32 v81, 0xbfb8aa3b, v81
	v_exp_f32_e32 v110, v81
	s_nop 0
	v_add_f32_e32 v81, 1.0, v110
	v_rcp_f32_e32 v108, v81
	v_med3_f32 v81, v93, s17, v231
	v_mul_f32_e32 v81, 0xbfb8aa3b, v81
	v_exp_f32_e32 v111, v81
	v_fma_f32 v64, v108, v112, v64
	v_add_f32_e32 v81, 1.0, v111
	v_rcp_f32_e32 v109, v81
	v_log_f32_e32 v64, v64
	v_fma_f32 v65, v109, v113, v65
	v_pk_mul_f32 v[110:111], v[110:111], v[108:109]
	v_mul_f32_e32 v81, 0x3f317217, v64
	v_fma_f32 v81, v64, s1, -v81
	v_fmac_f32_e32 v81, 0x3377d1cf, v64
	v_fmac_f32_e32 v81, 0x3f317217, v64
	v_cmp_lt_f32_e64 s[14:15], |v64|, s4
	v_pk_mul_f32 v[110:111], v[110:111], v[112:113]
	s_nop 0
	v_cndmask_b32_e64 v64, v64, v81, s[14:15]
	v_log_f32_e32 v65, v65
	s_nop 0
	v_mul_f32_e32 v81, 0x3f317217, v65
	v_fma_f32 v81, v65, s1, -v81
	v_fmac_f32_e32 v81, 0x3377d1cf, v65
	v_fmac_f32_e32 v81, 0x3f317217, v65
	v_cmp_lt_f32_e64 s[14:15], |v65|, s4
	s_nop 1
	v_cndmask_b32_e64 v65, v65, v81, s[14:15]
	v_med3_f32 v81, v94, s17, v231
	v_mul_f32_e32 v81, 0xbfb8aa3b, v81
	v_exp_f32_e32 v108, v81
	s_nop 0
	v_add_f32_e32 v81, 1.0, v108
	v_rcp_f32_e32 v112, v81
	v_med3_f32 v81, v95, s17, v231
	v_mul_f32_e32 v81, 0xbfb8aa3b, v81
	v_exp_f32_e32 v109, v81
	v_fma_f32 v66, v112, v114, v66
	v_add_f32_e32 v81, 1.0, v109
	v_rcp_f32_e32 v113, v81
	v_log_f32_e32 v66, v66
	v_fmac_f32_e32 v67, v113, v115
	v_pk_mul_f32 v[108:109], v[108:109], v[112:113]
	v_mul_f32_e32 v81, 0x3f317217, v66
	v_fma_f32 v81, v66, s1, -v81
	v_fmac_f32_e32 v81, 0x3377d1cf, v66
	v_fmac_f32_e32 v81, 0x3f317217, v66
	v_cmp_lt_f32_e64 s[14:15], |v66|, s4
	v_pk_mul_f32 v[108:109], v[108:109], v[114:115]
	s_nop 0
	v_cndmask_b32_e64 v66, v66, v81, s[14:15]
	v_log_f32_e32 v67, v67
	s_nop 0
	v_mul_f32_e32 v81, 0x3f317217, v67
	v_fma_f32 v81, v67, s1, -v81
	v_fmac_f32_e32 v81, 0x3377d1cf, v67
	v_fmac_f32_e32 v81, 0x3f317217, v67
	v_cmp_lt_f32_e64 s[14:15], |v67|, s4
	s_nop 1
	v_cndmask_b32_e64 v67, v67, v81, s[14:15]
	global_store_dwordx4 v[86:87], v[68:71], off
	global_store_dwordx4 v[86:87], v[64:67], off offset:16
	s_nop 0
	v_lshl_add_u64 v[68:69], v[98:99], 1, v[84:85]
	v_cvt_pk_bf16_f32 v64, v104, v105
	v_cvt_pk_bf16_f32 v65, v106, v107
	v_cvt_pk_bf16_f32 v66, v110, v111
	v_cvt_pk_bf16_f32 v67, v108, v109
	global_store_dwordx4 v[68:69], v[64:67], off
	s_mov_b64 s[14:15], 0
	s_branch .LBB0_804

.LBB0_820:
	s_andn2_b64 vcc, exec, s[14:15]
	s_cbranch_vccnz .LBB0_822
	v_lshl_add_u32 v72, s93, 8, v194
	v_ashrrev_i32_e32 v73, 31, v72
	v_lshlrev_b64 v[74:75], 2, v[72:73]
	v_lshl_add_u64 v[60:61], s[80:81], 0, v[74:75]
	global_load_dwordx4 v[56:59], v[60:61], off offset:16
	s_nop 0
	global_load_dwordx4 v[60:63], v[60:61], off
	s_mov_b32 s17, 0xc2700000
	v_med3_f32 v79, v76, s17, v231
	v_mul_f32_e32 v79, 0xbfb8aa3b, v79
	v_exp_f32_e32 v82, v79
	s_mov_b32 s1, 0x3f317217
	v_lshl_add_u64 v[74:75], v[70:71], 0, v[74:75]
	v_add_f32_e32 v79, 1.0, v82
	v_rcp_f32_e32 v90, v79
	v_med3_f32 v79, v77, s17, v231
	v_mul_f32_e32 v79, 0xbfb8aa3b, v79
	v_exp_f32_e32 v83, v79
	s_waitcnt vmcnt(0)
	v_pk_add_f32 v[98:99], v[56:57], 1.0 op_sel_hi:[1,0] neg_lo:[1,0] neg_hi:[1,0]
	v_pk_add_f32 v[92:93], v[60:61], 1.0 op_sel_hi:[1,0] neg_lo:[1,0] neg_hi:[1,0]
	v_add_f32_e32 v79, 1.0, v83
	v_fma_f32 v60, v90, v92, v60
	v_rcp_f32_e32 v91, v79
	v_pk_add_f32 v[94:95], v[62:63], 1.0 op_sel_hi:[1,0] neg_lo:[1,0] neg_hi:[1,0]
	v_log_f32_e32 v60, v60
	v_fma_f32 v61, v91, v93, v61
	v_pk_mul_f32 v[82:83], v[82:83], v[90:91]
	v_pk_add_f32 v[100:101], v[58:59], 1.0 op_sel_hi:[1,0] neg_lo:[1,0] neg_hi:[1,0]
	v_mul_f32_e32 v79, 0x3f317217, v60
	v_fma_f32 v79, v60, s1, -v79
	v_fmac_f32_e32 v79, 0x3377d1cf, v60
	v_fmac_f32_e32 v79, 0x3f317217, v60
	v_cmp_lt_f32_e64 s[14:15], |v60|, s4
	v_pk_mul_f32 v[82:83], v[82:83], v[92:93]
	s_nop 0
	v_cndmask_b32_e64 v60, v60, v79, s[14:15]
	v_log_f32_e32 v61, v61
	s_nop 0
	v_mul_f32_e32 v79, 0x3f317217, v61
	v_fma_f32 v79, v61, s1, -v79
	v_fmac_f32_e32 v79, 0x3377d1cf, v61
	v_fmac_f32_e32 v79, 0x3f317217, v61
	v_cmp_lt_f32_e64 s[14:15], |v61|, s4
	s_nop 1
	v_cndmask_b32_e64 v61, v61, v79, s[14:15]
	v_med3_f32 v79, v84, s17, v231
	v_mul_f32_e32 v79, 0xbfb8aa3b, v79
	v_exp_f32_e32 v90, v79
	s_nop 0
	v_add_f32_e32 v79, 1.0, v90
	v_rcp_f32_e32 v92, v79
	v_med3_f32 v79, v85, s17, v231
	v_mul_f32_e32 v79, 0xbfb8aa3b, v79
	v_exp_f32_e32 v91, v79
	v_fma_f32 v62, v92, v94, v62
	v_add_f32_e32 v79, 1.0, v91
	v_rcp_f32_e32 v93, v79
	v_log_f32_e32 v62, v62
	v_fmac_f32_e32 v63, v93, v95
	v_pk_mul_f32 v[90:91], v[90:91], v[92:93]
	v_mul_f32_e32 v79, 0x3f317217, v62
	v_fma_f32 v79, v62, s1, -v79
	v_fmac_f32_e32 v79, 0x3377d1cf, v62
	v_fmac_f32_e32 v79, 0x3f317217, v62
	v_cmp_lt_f32_e64 s[14:15], |v62|, s4
	v_pk_mul_f32 v[90:91], v[90:91], v[94:95]
	s_nop 0
	v_cndmask_b32_e64 v62, v62, v79, s[14:15]
	v_log_f32_e32 v63, v63
	s_nop 0
	v_mul_f32_e32 v79, 0x3f317217, v63
	v_fma_f32 v79, v63, s1, -v79
	v_fmac_f32_e32 v79, 0x3377d1cf, v63
	v_fmac_f32_e32 v79, 0x3f317217, v63
	v_cmp_lt_f32_e64 s[14:15], |v63|, s4
	s_nop 1
	v_cndmask_b32_e64 v63, v63, v79, s[14:15]
	v_med3_f32 v79, v86, s17, v231
	v_mul_f32_e32 v79, 0xbfb8aa3b, v79
	v_exp_f32_e32 v94, v79
	s_nop 0
	v_add_f32_e32 v79, 1.0, v94
	v_rcp_f32_e32 v92, v79
	v_med3_f32 v79, v87, s17, v231
	v_mul_f32_e32 v79, 0xbfb8aa3b, v79
	v_exp_f32_e32 v95, v79
	v_fma_f32 v56, v92, v98, v56
	v_add_f32_e32 v79, 1.0, v95
	v_rcp_f32_e32 v93, v79
	v_log_f32_e32 v56, v56
	v_fma_f32 v57, v93, v99, v57
	v_pk_mul_f32 v[94:95], v[94:95], v[92:93]
	v_mul_f32_e32 v79, 0x3f317217, v56
	v_fma_f32 v79, v56, s1, -v79
	v_fmac_f32_e32 v79, 0x3377d1cf, v56
	v_fmac_f32_e32 v79, 0x3f317217, v56
	v_cmp_lt_f32_e64 s[14:15], |v56|, s4
	v_pk_mul_f32 v[94:95], v[94:95], v[98:99]
	s_nop 0
	v_cndmask_b32_e64 v56, v56, v79, s[14:15]
	v_log_f32_e32 v57, v57
	s_nop 0
	v_mul_f32_e32 v79, 0x3f317217, v57
	v_fma_f32 v79, v57, s1, -v79
	v_fmac_f32_e32 v79, 0x3377d1cf, v57
	v_fmac_f32_e32 v79, 0x3f317217, v57
	v_cmp_lt_f32_e64 s[14:15], |v57|, s4
	s_nop 1
	v_cndmask_b32_e64 v57, v57, v79, s[14:15]
	v_med3_f32 v79, v88, s17, v231
	v_mul_f32_e32 v79, 0xbfb8aa3b, v79
	v_exp_f32_e32 v92, v79
	s_nop 0
	v_add_f32_e32 v79, 1.0, v92
	v_rcp_f32_e32 v98, v79
	v_med3_f32 v79, v89, s17, v231
	v_mul_f32_e32 v79, 0xbfb8aa3b, v79
	v_exp_f32_e32 v93, v79
	v_fma_f32 v58, v98, v100, v58
	v_add_f32_e32 v79, 1.0, v93
	v_rcp_f32_e32 v99, v79
	v_log_f32_e32 v58, v58
	v_fmac_f32_e32 v59, v99, v101
	v_pk_mul_f32 v[92:93], v[92:93], v[98:99]
	v_mul_f32_e32 v79, 0x3f317217, v58
	v_fma_f32 v79, v58, s1, -v79
	v_fmac_f32_e32 v79, 0x3377d1cf, v58
	v_fmac_f32_e32 v79, 0x3f317217, v58
	v_cmp_lt_f32_e64 s[14:15], |v58|, s4
	v_pk_mul_f32 v[92:93], v[92:93], v[100:101]
	s_nop 0
	v_cndmask_b32_e64 v58, v58, v79, s[14:15]
	v_log_f32_e32 v59, v59
	s_nop 0
	v_mul_f32_e32 v79, 0x3f317217, v59
	v_fma_f32 v79, v59, s1, -v79
	v_fmac_f32_e32 v79, 0x3377d1cf, v59
	v_fmac_f32_e32 v79, 0x3f317217, v59
	v_cmp_lt_f32_e64 s[14:15], |v59|, s4
	s_nop 1
	v_cndmask_b32_e64 v59, v59, v79, s[14:15]
	global_store_dwordx4 v[74:75], v[60:63], off
	global_store_dwordx4 v[74:75], v[56:59], off offset:16
	s_nop 0
	v_lshl_add_u64 v[60:61], v[72:73], 1, v[68:69]
	v_cvt_pk_bf16_f32 v56, v82, v83
	v_cvt_pk_bf16_f32 v57, v90, v91
	v_cvt_pk_bf16_f32 v58, v94, v95
	v_cvt_pk_bf16_f32 v59, v92, v93
	global_store_dwordx4 v[60:61], v[56:59], off

.LBB0_852:
	s_andn2_b64 vcc, exec, s[14:15]
	s_cbranch_vccnz .LBB0_854
	v_lshl_add_u32 v80, s95, 7, v194
	v_ashrrev_i32_e32 v81, 31, v80
	v_lshlrev_b64 v[84:85], 2, v[80:81]
	v_lshl_add_u64 v[52:53], s[80:81], 0, v[84:85]
	global_load_dwordx4 v[48:51], v[52:53], off offset:16
	s_nop 0
	global_load_dwordx4 v[52:55], v[52:53], off
	s_mov_b32 s17, 0xc2700000
	v_med3_f32 v65, v56, s17, v231
	v_mul_f32_e32 v65, 0xbfb8aa3b, v65
	v_exp_f32_e32 v86, v65
	s_mov_b32 s1, 0x3f317217
	v_lshl_add_u64 v[70:71], v[70:71], 0, v[84:85]
	v_add_f32_e32 v65, 1.0, v86
	v_rcp_f32_e32 v88, v65
	v_med3_f32 v65, v57, s17, v231
	v_mul_f32_e32 v65, 0xbfb8aa3b, v65
	v_exp_f32_e32 v87, v65
	s_waitcnt vmcnt(0)
	v_pk_add_f32 v[94:95], v[48:49], 1.0 op_sel_hi:[1,0] neg_lo:[1,0] neg_hi:[1,0]
	v_pk_add_f32 v[90:91], v[52:53], 1.0 op_sel_hi:[1,0] neg_lo:[1,0] neg_hi:[1,0]
	v_add_f32_e32 v65, 1.0, v87
	v_fma_f32 v52, v88, v90, v52
	v_rcp_f32_e32 v89, v65
	v_pk_add_f32 v[92:93], v[54:55], 1.0 op_sel_hi:[1,0] neg_lo:[1,0] neg_hi:[1,0]
	v_log_f32_e32 v52, v52
	v_fma_f32 v53, v89, v91, v53
	v_pk_mul_f32 v[86:87], v[86:87], v[88:89]
	v_pk_add_f32 v[98:99], v[50:51], 1.0 op_sel_hi:[1,0] neg_lo:[1,0] neg_hi:[1,0]
	v_mul_f32_e32 v65, 0x3f317217, v52
	v_fma_f32 v65, v52, s1, -v65
	v_fmac_f32_e32 v65, 0x3377d1cf, v52
	v_fmac_f32_e32 v65, 0x3f317217, v52
	v_cmp_lt_f32_e64 s[14:15], |v52|, s4
	v_pk_mul_f32 v[86:87], v[86:87], v[90:91]
	s_nop 0
	v_cndmask_b32_e64 v52, v52, v65, s[14:15]
	v_log_f32_e32 v53, v53
	s_nop 0
	v_mul_f32_e32 v65, 0x3f317217, v53
	v_fma_f32 v65, v53, s1, -v65
	v_fmac_f32_e32 v65, 0x3377d1cf, v53
	v_fmac_f32_e32 v65, 0x3f317217, v53
	v_cmp_lt_f32_e64 s[14:15], |v53|, s4
	s_nop 1
	v_cndmask_b32_e64 v53, v53, v65, s[14:15]
	v_med3_f32 v65, v58, s17, v231
	v_mul_f32_e32 v65, 0xbfb8aa3b, v65
	v_exp_f32_e32 v88, v65
	s_nop 0
	v_add_f32_e32 v65, 1.0, v88
	v_rcp_f32_e32 v90, v65
	v_med3_f32 v65, v59, s17, v231
	v_mul_f32_e32 v65, 0xbfb8aa3b, v65
	v_exp_f32_e32 v89, v65
	v_fma_f32 v54, v90, v92, v54
	v_add_f32_e32 v65, 1.0, v89
	v_rcp_f32_e32 v91, v65
	v_log_f32_e32 v54, v54
	v_fmac_f32_e32 v55, v91, v93
	v_pk_mul_f32 v[88:89], v[88:89], v[90:91]
	v_mul_f32_e32 v65, 0x3f317217, v54
	v_fma_f32 v65, v54, s1, -v65
	v_fmac_f32_e32 v65, 0x3377d1cf, v54
	v_fmac_f32_e32 v65, 0x3f317217, v54
	v_cmp_lt_f32_e64 s[14:15], |v54|, s4
	v_pk_mul_f32 v[88:89], v[88:89], v[92:93]
	s_nop 0
	v_cndmask_b32_e64 v54, v54, v65, s[14:15]
	v_log_f32_e32 v55, v55
	s_nop 0
	v_mul_f32_e32 v65, 0x3f317217, v55
	v_fma_f32 v65, v55, s1, -v65
	v_fmac_f32_e32 v65, 0x3377d1cf, v55
	v_fmac_f32_e32 v65, 0x3f317217, v55
	v_cmp_lt_f32_e64 s[14:15], |v55|, s4
	s_nop 1
	v_cndmask_b32_e64 v55, v55, v65, s[14:15]
	v_med3_f32 v65, v76, s17, v231
	v_mul_f32_e32 v65, 0xbfb8aa3b, v65
	v_exp_f32_e32 v92, v65
	s_nop 0
	v_add_f32_e32 v65, 1.0, v92
	v_rcp_f32_e32 v90, v65
	v_med3_f32 v65, v77, s17, v231
	v_mul_f32_e32 v65, 0xbfb8aa3b, v65
	v_exp_f32_e32 v93, v65
	v_fma_f32 v48, v90, v94, v48
	v_add_f32_e32 v65, 1.0, v93
	v_rcp_f32_e32 v91, v65
	v_log_f32_e32 v48, v48
	v_fma_f32 v49, v91, v95, v49
	v_pk_mul_f32 v[92:93], v[92:93], v[90:91]
	v_mul_f32_e32 v65, 0x3f317217, v48
	v_fma_f32 v65, v48, s1, -v65
	v_fmac_f32_e32 v65, 0x3377d1cf, v48
	v_fmac_f32_e32 v65, 0x3f317217, v48
	v_cmp_lt_f32_e64 s[14:15], |v48|, s4
	v_pk_mul_f32 v[92:93], v[92:93], v[94:95]
	s_nop 0
	v_cndmask_b32_e64 v48, v48, v65, s[14:15]
	v_log_f32_e32 v49, v49
	s_nop 0
	v_mul_f32_e32 v65, 0x3f317217, v49
	v_fma_f32 v65, v49, s1, -v65
	v_fmac_f32_e32 v65, 0x3377d1cf, v49
	v_fmac_f32_e32 v65, 0x3f317217, v49
	v_cmp_lt_f32_e64 s[14:15], |v49|, s4
	s_nop 1
	v_cndmask_b32_e64 v49, v49, v65, s[14:15]
	v_med3_f32 v65, v78, s17, v231
	v_mul_f32_e32 v65, 0xbfb8aa3b, v65
	v_exp_f32_e32 v90, v65
	s_nop 0
	v_add_f32_e32 v65, 1.0, v90
	v_rcp_f32_e32 v94, v65
	v_med3_f32 v65, v79, s17, v231
	v_mul_f32_e32 v65, 0xbfb8aa3b, v65
	v_exp_f32_e32 v91, v65
	v_fma_f32 v50, v94, v98, v50
	v_add_f32_e32 v65, 1.0, v91
	v_rcp_f32_e32 v95, v65
	v_log_f32_e32 v50, v50
	v_fmac_f32_e32 v51, v95, v99
	v_pk_mul_f32 v[90:91], v[90:91], v[94:95]
	v_mul_f32_e32 v65, 0x3f317217, v50
	v_fma_f32 v65, v50, s1, -v65
	v_fmac_f32_e32 v65, 0x3377d1cf, v50
	v_fmac_f32_e32 v65, 0x3f317217, v50
	v_cmp_lt_f32_e64 s[14:15], |v50|, s4
	v_pk_mul_f32 v[90:91], v[90:91], v[98:99]
	s_nop 0
	v_cndmask_b32_e64 v50, v50, v65, s[14:15]
	v_log_f32_e32 v51, v51
	s_nop 0
	v_mul_f32_e32 v65, 0x3f317217, v51
	v_fma_f32 v65, v51, s1, -v65
	v_fmac_f32_e32 v65, 0x3377d1cf, v51
	v_fmac_f32_e32 v65, 0x3f317217, v51
	v_cmp_lt_f32_e64 s[14:15], |v51|, s4
	s_nop 1
	v_cndmask_b32_e64 v51, v51, v65, s[14:15]
	global_store_dwordx4 v[70:71], v[52:55], off
	global_store_dwordx4 v[70:71], v[48:51], off offset:16
	s_nop 0
	v_lshl_add_u64 v[52:53], v[80:81], 1, v[68:69]
	v_cvt_pk_bf16_f32 v48, v86, v87
	v_cvt_pk_bf16_f32 v49, v88, v89
	v_cvt_pk_bf16_f32 v50, v92, v93
	v_cvt_pk_bf16_f32 v51, v90, v91
	global_store_dwordx4 v[52:53], v[48:51], off
	s_mov_b64 s[14:15], 0
	s_branch .LBB0_871

.LBB0_887:
	s_andn2_b64 vcc, exec, s[14:15]
	s_cbranch_vccnz .LBB0_889
	v_lshl_add_u32 v56, s93, 8, v194
	v_ashrrev_i32_e32 v57, 31, v56
	v_lshlrev_b64 v[58:59], 2, v[56:57]
	v_lshl_add_u64 v[44:45], s[80:81], 0, v[58:59]
	global_load_dwordx4 v[40:43], v[44:45], off offset:16
	s_nop 0
	global_load_dwordx4 v[44:47], v[44:45], off
	s_mov_b32 s17, 0xc2700000
	v_med3_f32 v63, v60, s17, v231
	v_mul_f32_e32 v63, 0xbfb8aa3b, v63
	v_exp_f32_e32 v66, v63
	s_mov_b32 s1, 0x3f317217
	v_lshl_add_u64 v[58:59], v[54:55], 0, v[58:59]
	v_add_f32_e32 v63, 1.0, v66
	v_rcp_f32_e32 v74, v63
	v_med3_f32 v63, v61, s17, v231
	v_mul_f32_e32 v63, 0xbfb8aa3b, v63
	v_exp_f32_e32 v67, v63
	s_waitcnt vmcnt(0)
	v_pk_add_f32 v[80:81], v[40:41], 1.0 op_sel_hi:[1,0] neg_lo:[1,0] neg_hi:[1,0]
	v_pk_add_f32 v[76:77], v[44:45], 1.0 op_sel_hi:[1,0] neg_lo:[1,0] neg_hi:[1,0]
	v_add_f32_e32 v63, 1.0, v67
	v_fma_f32 v44, v74, v76, v44
	v_rcp_f32_e32 v75, v63
	v_pk_add_f32 v[78:79], v[46:47], 1.0 op_sel_hi:[1,0] neg_lo:[1,0] neg_hi:[1,0]
	v_log_f32_e32 v44, v44
	v_fma_f32 v45, v75, v77, v45
	v_pk_mul_f32 v[66:67], v[66:67], v[74:75]
	v_pk_add_f32 v[82:83], v[42:43], 1.0 op_sel_hi:[1,0] neg_lo:[1,0] neg_hi:[1,0]
	v_mul_f32_e32 v63, 0x3f317217, v44
	v_fma_f32 v63, v44, s1, -v63
	v_fmac_f32_e32 v63, 0x3377d1cf, v44
	v_fmac_f32_e32 v63, 0x3f317217, v44
	v_cmp_lt_f32_e64 s[14:15], |v44|, s4
	v_pk_mul_f32 v[66:67], v[66:67], v[76:77]
	s_nop 0
	v_cndmask_b32_e64 v44, v44, v63, s[14:15]
	v_log_f32_e32 v45, v45
	s_nop 0
	v_mul_f32_e32 v63, 0x3f317217, v45
	v_fma_f32 v63, v45, s1, -v63
	v_fmac_f32_e32 v63, 0x3377d1cf, v45
	v_fmac_f32_e32 v63, 0x3f317217, v45
	v_cmp_lt_f32_e64 s[14:15], |v45|, s4
	s_nop 1
	v_cndmask_b32_e64 v45, v45, v63, s[14:15]
	v_med3_f32 v63, v68, s17, v231
	v_mul_f32_e32 v63, 0xbfb8aa3b, v63
	v_exp_f32_e32 v74, v63
	s_nop 0
	v_add_f32_e32 v63, 1.0, v74
	v_rcp_f32_e32 v76, v63
	v_med3_f32 v63, v69, s17, v231
	v_mul_f32_e32 v63, 0xbfb8aa3b, v63
	v_exp_f32_e32 v75, v63
	v_fma_f32 v46, v76, v78, v46
	v_add_f32_e32 v63, 1.0, v75
	v_rcp_f32_e32 v77, v63
	v_log_f32_e32 v46, v46
	v_fmac_f32_e32 v47, v77, v79
	v_pk_mul_f32 v[74:75], v[74:75], v[76:77]
	v_mul_f32_e32 v63, 0x3f317217, v46
	v_fma_f32 v63, v46, s1, -v63
	v_fmac_f32_e32 v63, 0x3377d1cf, v46
	v_fmac_f32_e32 v63, 0x3f317217, v46
	v_cmp_lt_f32_e64 s[14:15], |v46|, s4
	v_pk_mul_f32 v[74:75], v[74:75], v[78:79]
	s_nop 0
	v_cndmask_b32_e64 v46, v46, v63, s[14:15]
	v_log_f32_e32 v47, v47
	s_nop 0
	v_mul_f32_e32 v63, 0x3f317217, v47
	v_fma_f32 v63, v47, s1, -v63
	v_fmac_f32_e32 v63, 0x3377d1cf, v47
	v_fmac_f32_e32 v63, 0x3f317217, v47
	v_cmp_lt_f32_e64 s[14:15], |v47|, s4
	s_nop 1
	v_cndmask_b32_e64 v47, v47, v63, s[14:15]
	v_med3_f32 v63, v70, s17, v231
	v_mul_f32_e32 v63, 0xbfb8aa3b, v63
	v_exp_f32_e32 v78, v63
	s_nop 0
	v_add_f32_e32 v63, 1.0, v78
	v_rcp_f32_e32 v76, v63
	v_med3_f32 v63, v71, s17, v231
	v_mul_f32_e32 v63, 0xbfb8aa3b, v63
	v_exp_f32_e32 v79, v63
	v_fma_f32 v40, v76, v80, v40
	v_add_f32_e32 v63, 1.0, v79
	v_rcp_f32_e32 v77, v63
	v_log_f32_e32 v40, v40
	v_fma_f32 v41, v77, v81, v41
	v_pk_mul_f32 v[78:79], v[78:79], v[76:77]
	v_mul_f32_e32 v63, 0x3f317217, v40
	v_fma_f32 v63, v40, s1, -v63
	v_fmac_f32_e32 v63, 0x3377d1cf, v40
	v_fmac_f32_e32 v63, 0x3f317217, v40
	v_cmp_lt_f32_e64 s[14:15], |v40|, s4
	v_pk_mul_f32 v[78:79], v[78:79], v[80:81]
	s_nop 0
	v_cndmask_b32_e64 v40, v40, v63, s[14:15]
	v_log_f32_e32 v41, v41
	s_nop 0
	v_mul_f32_e32 v63, 0x3f317217, v41
	v_fma_f32 v63, v41, s1, -v63
	v_fmac_f32_e32 v63, 0x3377d1cf, v41
	v_fmac_f32_e32 v63, 0x3f317217, v41
	v_cmp_lt_f32_e64 s[14:15], |v41|, s4
	s_nop 1
	v_cndmask_b32_e64 v41, v41, v63, s[14:15]
	v_med3_f32 v63, v72, s17, v231
	v_mul_f32_e32 v63, 0xbfb8aa3b, v63
	v_exp_f32_e32 v76, v63
	s_nop 0
	v_add_f32_e32 v63, 1.0, v76
	v_rcp_f32_e32 v80, v63
	v_med3_f32 v63, v73, s17, v231
	v_mul_f32_e32 v63, 0xbfb8aa3b, v63
	v_exp_f32_e32 v77, v63
	v_fma_f32 v42, v80, v82, v42
	v_add_f32_e32 v63, 1.0, v77
	v_rcp_f32_e32 v81, v63
	v_log_f32_e32 v42, v42
	v_fmac_f32_e32 v43, v81, v83
	v_pk_mul_f32 v[76:77], v[76:77], v[80:81]
	v_mul_f32_e32 v63, 0x3f317217, v42
	v_fma_f32 v63, v42, s1, -v63
	v_fmac_f32_e32 v63, 0x3377d1cf, v42
	v_fmac_f32_e32 v63, 0x3f317217, v42
	v_cmp_lt_f32_e64 s[14:15], |v42|, s4
	v_pk_mul_f32 v[76:77], v[76:77], v[82:83]
	s_nop 0
	v_cndmask_b32_e64 v42, v42, v63, s[14:15]
	v_log_f32_e32 v43, v43
	s_nop 0
	v_mul_f32_e32 v63, 0x3f317217, v43
	v_fma_f32 v63, v43, s1, -v63
	v_fmac_f32_e32 v63, 0x3377d1cf, v43
	v_fmac_f32_e32 v63, 0x3f317217, v43
	v_cmp_lt_f32_e64 s[14:15], |v43|, s4
	s_nop 1
	v_cndmask_b32_e64 v43, v43, v63, s[14:15]
	global_store_dwordx4 v[58:59], v[44:47], off
	global_store_dwordx4 v[58:59], v[40:43], off offset:16
	s_nop 0
	v_lshl_add_u64 v[44:45], v[56:57], 1, v[52:53]
	v_cvt_pk_bf16_f32 v40, v66, v67
	v_cvt_pk_bf16_f32 v41, v74, v75
	v_cvt_pk_bf16_f32 v42, v78, v79
	v_cvt_pk_bf16_f32 v43, v76, v77
	global_store_dwordx4 v[44:45], v[40:43], off

.LBB0_919:
	s_andn2_b64 vcc, exec, s[14:15]
	s_cbranch_vccnz .LBB0_921
	v_lshl_add_u32 v64, s95, 7, v194
	v_ashrrev_i32_e32 v65, 31, v64
	v_lshlrev_b64 v[68:69], 2, v[64:65]
	v_lshl_add_u64 v[36:37], s[80:81], 0, v[68:69]
	global_load_dwordx4 v[32:35], v[36:37], off offset:16
	s_nop 0
	global_load_dwordx4 v[36:39], v[36:37], off
	s_mov_b32 s17, 0xc2700000
	v_med3_f32 v49, v40, s17, v231
	v_mul_f32_e32 v49, 0xbfb8aa3b, v49
	v_exp_f32_e32 v70, v49
	s_mov_b32 s1, 0x3f317217
	v_lshl_add_u64 v[54:55], v[54:55], 0, v[68:69]
	v_add_f32_e32 v49, 1.0, v70
	v_rcp_f32_e32 v72, v49
	v_med3_f32 v49, v41, s17, v231
	v_mul_f32_e32 v49, 0xbfb8aa3b, v49
	v_exp_f32_e32 v71, v49
	s_waitcnt vmcnt(0)
	v_pk_add_f32 v[78:79], v[32:33], 1.0 op_sel_hi:[1,0] neg_lo:[1,0] neg_hi:[1,0]
	v_pk_add_f32 v[74:75], v[36:37], 1.0 op_sel_hi:[1,0] neg_lo:[1,0] neg_hi:[1,0]
	v_add_f32_e32 v49, 1.0, v71
	v_fma_f32 v36, v72, v74, v36
	v_rcp_f32_e32 v73, v49
	v_pk_add_f32 v[76:77], v[38:39], 1.0 op_sel_hi:[1,0] neg_lo:[1,0] neg_hi:[1,0]
	v_log_f32_e32 v36, v36
	v_fma_f32 v37, v73, v75, v37
	v_pk_mul_f32 v[70:71], v[70:71], v[72:73]
	v_pk_add_f32 v[80:81], v[34:35], 1.0 op_sel_hi:[1,0] neg_lo:[1,0] neg_hi:[1,0]
	v_mul_f32_e32 v49, 0x3f317217, v36
	v_fma_f32 v49, v36, s1, -v49
	v_fmac_f32_e32 v49, 0x3377d1cf, v36
	v_fmac_f32_e32 v49, 0x3f317217, v36
	v_cmp_lt_f32_e64 s[14:15], |v36|, s4
	v_pk_mul_f32 v[70:71], v[70:71], v[74:75]
	s_nop 0
	v_cndmask_b32_e64 v36, v36, v49, s[14:15]
	v_log_f32_e32 v37, v37
	s_nop 0
	v_mul_f32_e32 v49, 0x3f317217, v37
	v_fma_f32 v49, v37, s1, -v49
	v_fmac_f32_e32 v49, 0x3377d1cf, v37
	v_fmac_f32_e32 v49, 0x3f317217, v37
	v_cmp_lt_f32_e64 s[14:15], |v37|, s4
	s_nop 1
	v_cndmask_b32_e64 v37, v37, v49, s[14:15]
	v_med3_f32 v49, v42, s17, v231
	v_mul_f32_e32 v49, 0xbfb8aa3b, v49
	v_exp_f32_e32 v72, v49
	s_nop 0
	v_add_f32_e32 v49, 1.0, v72
	v_rcp_f32_e32 v74, v49
	v_med3_f32 v49, v43, s17, v231
	v_mul_f32_e32 v49, 0xbfb8aa3b, v49
	v_exp_f32_e32 v73, v49
	v_fma_f32 v38, v74, v76, v38
	v_add_f32_e32 v49, 1.0, v73
	v_rcp_f32_e32 v75, v49
	v_log_f32_e32 v38, v38
	v_fmac_f32_e32 v39, v75, v77
	v_pk_mul_f32 v[72:73], v[72:73], v[74:75]
	v_mul_f32_e32 v49, 0x3f317217, v38
	v_fma_f32 v49, v38, s1, -v49
	v_fmac_f32_e32 v49, 0x3377d1cf, v38
	v_fmac_f32_e32 v49, 0x3f317217, v38
	v_cmp_lt_f32_e64 s[14:15], |v38|, s4
	v_pk_mul_f32 v[72:73], v[72:73], v[76:77]
	s_nop 0
	v_cndmask_b32_e64 v38, v38, v49, s[14:15]
	v_log_f32_e32 v39, v39
	s_nop 0
	v_mul_f32_e32 v49, 0x3f317217, v39
	v_fma_f32 v49, v39, s1, -v49
	v_fmac_f32_e32 v49, 0x3377d1cf, v39
	v_fmac_f32_e32 v49, 0x3f317217, v39
	v_cmp_lt_f32_e64 s[14:15], |v39|, s4
	s_nop 1
	v_cndmask_b32_e64 v39, v39, v49, s[14:15]
	v_med3_f32 v49, v60, s17, v231
	v_mul_f32_e32 v49, 0xbfb8aa3b, v49
	v_exp_f32_e32 v76, v49
	s_nop 0
	v_add_f32_e32 v49, 1.0, v76
	v_rcp_f32_e32 v74, v49
	v_med3_f32 v49, v61, s17, v231
	v_mul_f32_e32 v49, 0xbfb8aa3b, v49
	v_exp_f32_e32 v77, v49
	v_fma_f32 v32, v74, v78, v32
	v_add_f32_e32 v49, 1.0, v77
	v_rcp_f32_e32 v75, v49
	v_log_f32_e32 v32, v32
	v_fma_f32 v33, v75, v79, v33
	v_pk_mul_f32 v[76:77], v[76:77], v[74:75]
	v_mul_f32_e32 v49, 0x3f317217, v32
	v_fma_f32 v49, v32, s1, -v49
	v_fmac_f32_e32 v49, 0x3377d1cf, v32
	v_fmac_f32_e32 v49, 0x3f317217, v32
	v_cmp_lt_f32_e64 s[14:15], |v32|, s4
	v_pk_mul_f32 v[76:77], v[76:77], v[78:79]
	s_nop 0
	v_cndmask_b32_e64 v32, v32, v49, s[14:15]
	v_log_f32_e32 v33, v33
	s_nop 0
	v_mul_f32_e32 v49, 0x3f317217, v33
	v_fma_f32 v49, v33, s1, -v49
	v_fmac_f32_e32 v49, 0x3377d1cf, v33
	v_fmac_f32_e32 v49, 0x3f317217, v33
	v_cmp_lt_f32_e64 s[14:15], |v33|, s4
	s_nop 1
	v_cndmask_b32_e64 v33, v33, v49, s[14:15]
	v_med3_f32 v49, v62, s17, v231
	v_mul_f32_e32 v49, 0xbfb8aa3b, v49
	v_exp_f32_e32 v74, v49
	s_nop 0
	v_add_f32_e32 v49, 1.0, v74
	v_rcp_f32_e32 v78, v49
	v_med3_f32 v49, v63, s17, v231
	v_mul_f32_e32 v49, 0xbfb8aa3b, v49
	v_exp_f32_e32 v75, v49
	v_fma_f32 v34, v78, v80, v34
	v_add_f32_e32 v49, 1.0, v75
	v_rcp_f32_e32 v79, v49
	v_log_f32_e32 v34, v34
	v_fmac_f32_e32 v35, v79, v81
	v_pk_mul_f32 v[74:75], v[74:75], v[78:79]
	v_mul_f32_e32 v49, 0x3f317217, v34
	v_fma_f32 v49, v34, s1, -v49
	v_fmac_f32_e32 v49, 0x3377d1cf, v34
	v_fmac_f32_e32 v49, 0x3f317217, v34
	v_cmp_lt_f32_e64 s[14:15], |v34|, s4
	v_pk_mul_f32 v[74:75], v[74:75], v[80:81]
	s_nop 0
	v_cndmask_b32_e64 v34, v34, v49, s[14:15]
	v_log_f32_e32 v35, v35
	s_nop 0
	v_mul_f32_e32 v49, 0x3f317217, v35
	v_fma_f32 v49, v35, s1, -v49
	v_fmac_f32_e32 v49, 0x3377d1cf, v35
	v_fmac_f32_e32 v49, 0x3f317217, v35
	v_cmp_lt_f32_e64 s[14:15], |v35|, s4
	s_nop 1
	v_cndmask_b32_e64 v35, v35, v49, s[14:15]
	global_store_dwordx4 v[54:55], v[36:39], off
	global_store_dwordx4 v[54:55], v[32:35], off offset:16
	s_nop 0
	v_lshl_add_u64 v[36:37], v[64:65], 1, v[52:53]
	v_cvt_pk_bf16_f32 v32, v70, v71
	v_cvt_pk_bf16_f32 v33, v72, v73
	v_cvt_pk_bf16_f32 v34, v76, v77
	v_cvt_pk_bf16_f32 v35, v74, v75
	global_store_dwordx4 v[36:37], v[32:35], off
	s_mov_b64 s[14:15], 0
	s_branch .LBB0_938

.LBB0_954:
	s_andn2_b64 vcc, exec, s[14:15]
	s_cbranch_vccnz .LBB0_956
	v_lshl_add_u32 v40, s93, 8, v194
	v_ashrrev_i32_e32 v41, 31, v40
	v_lshlrev_b64 v[42:43], 2, v[40:41]
	v_lshl_add_u64 v[28:29], s[80:81], 0, v[42:43]
	global_load_dwordx4 v[24:27], v[28:29], off offset:16
	s_nop 0
	global_load_dwordx4 v[28:31], v[28:29], off
	s_mov_b32 s17, 0xc2700000
	v_med3_f32 v47, v44, s17, v231
	v_mul_f32_e32 v47, 0xbfb8aa3b, v47
	v_exp_f32_e32 v50, v47
	s_mov_b32 s1, 0x3f317217
	v_lshl_add_u64 v[42:43], v[38:39], 0, v[42:43]
	v_add_f32_e32 v47, 1.0, v50
	v_rcp_f32_e32 v58, v47
	v_med3_f32 v47, v45, s17, v231
	v_mul_f32_e32 v47, 0xbfb8aa3b, v47
	v_exp_f32_e32 v51, v47
	s_waitcnt vmcnt(0)
	v_pk_add_f32 v[64:65], v[24:25], 1.0 op_sel_hi:[1,0] neg_lo:[1,0] neg_hi:[1,0]
	v_pk_add_f32 v[60:61], v[28:29], 1.0 op_sel_hi:[1,0] neg_lo:[1,0] neg_hi:[1,0]
	v_add_f32_e32 v47, 1.0, v51
	v_fma_f32 v28, v58, v60, v28
	v_rcp_f32_e32 v59, v47
	v_pk_add_f32 v[62:63], v[30:31], 1.0 op_sel_hi:[1,0] neg_lo:[1,0] neg_hi:[1,0]
	v_log_f32_e32 v28, v28
	v_fma_f32 v29, v59, v61, v29
	v_pk_mul_f32 v[50:51], v[50:51], v[58:59]
	v_pk_add_f32 v[66:67], v[26:27], 1.0 op_sel_hi:[1,0] neg_lo:[1,0] neg_hi:[1,0]
	v_mul_f32_e32 v47, 0x3f317217, v28
	v_fma_f32 v47, v28, s1, -v47
	v_fmac_f32_e32 v47, 0x3377d1cf, v28
	v_fmac_f32_e32 v47, 0x3f317217, v28
	v_cmp_lt_f32_e64 s[14:15], |v28|, s4
	v_pk_mul_f32 v[50:51], v[50:51], v[60:61]
	s_nop 0
	v_cndmask_b32_e64 v28, v28, v47, s[14:15]
	v_log_f32_e32 v29, v29
	s_nop 0
	v_mul_f32_e32 v47, 0x3f317217, v29
	v_fma_f32 v47, v29, s1, -v47
	v_fmac_f32_e32 v47, 0x3377d1cf, v29
	v_fmac_f32_e32 v47, 0x3f317217, v29
	v_cmp_lt_f32_e64 s[14:15], |v29|, s4
	s_nop 1
	v_cndmask_b32_e64 v29, v29, v47, s[14:15]
	v_med3_f32 v47, v52, s17, v231
	v_mul_f32_e32 v47, 0xbfb8aa3b, v47
	v_exp_f32_e32 v58, v47
	s_nop 0
	v_add_f32_e32 v47, 1.0, v58
	v_rcp_f32_e32 v60, v47
	v_med3_f32 v47, v53, s17, v231
	v_mul_f32_e32 v47, 0xbfb8aa3b, v47
	v_exp_f32_e32 v59, v47
	v_fma_f32 v30, v60, v62, v30
	v_add_f32_e32 v47, 1.0, v59
	v_rcp_f32_e32 v61, v47
	v_log_f32_e32 v30, v30
	v_fmac_f32_e32 v31, v61, v63
	v_pk_mul_f32 v[58:59], v[58:59], v[60:61]
	v_mul_f32_e32 v47, 0x3f317217, v30
	v_fma_f32 v47, v30, s1, -v47
	v_fmac_f32_e32 v47, 0x3377d1cf, v30
	v_fmac_f32_e32 v47, 0x3f317217, v30
	v_cmp_lt_f32_e64 s[14:15], |v30|, s4
	v_pk_mul_f32 v[58:59], v[58:59], v[62:63]
	s_nop 0
	v_cndmask_b32_e64 v30, v30, v47, s[14:15]
	v_log_f32_e32 v31, v31
	s_nop 0
	v_mul_f32_e32 v47, 0x3f317217, v31
	v_fma_f32 v47, v31, s1, -v47
	v_fmac_f32_e32 v47, 0x3377d1cf, v31
	v_fmac_f32_e32 v47, 0x3f317217, v31
	v_cmp_lt_f32_e64 s[14:15], |v31|, s4
	s_nop 1
	v_cndmask_b32_e64 v31, v31, v47, s[14:15]
	v_med3_f32 v47, v54, s17, v231
	v_mul_f32_e32 v47, 0xbfb8aa3b, v47
	v_exp_f32_e32 v62, v47
	s_nop 0
	v_add_f32_e32 v47, 1.0, v62
	v_rcp_f32_e32 v60, v47
	v_med3_f32 v47, v55, s17, v231
	v_mul_f32_e32 v47, 0xbfb8aa3b, v47
	v_exp_f32_e32 v63, v47
	v_fma_f32 v24, v60, v64, v24
	v_add_f32_e32 v47, 1.0, v63
	v_rcp_f32_e32 v61, v47
	v_log_f32_e32 v24, v24
	v_fma_f32 v25, v61, v65, v25
	v_pk_mul_f32 v[62:63], v[62:63], v[60:61]
	v_mul_f32_e32 v47, 0x3f317217, v24
	v_fma_f32 v47, v24, s1, -v47
	v_fmac_f32_e32 v47, 0x3377d1cf, v24
	v_fmac_f32_e32 v47, 0x3f317217, v24
	v_cmp_lt_f32_e64 s[14:15], |v24|, s4
	v_pk_mul_f32 v[62:63], v[62:63], v[64:65]
	s_nop 0
	v_cndmask_b32_e64 v24, v24, v47, s[14:15]
	v_log_f32_e32 v25, v25
	s_nop 0
	v_mul_f32_e32 v47, 0x3f317217, v25
	v_fma_f32 v47, v25, s1, -v47
	v_fmac_f32_e32 v47, 0x3377d1cf, v25
	v_fmac_f32_e32 v47, 0x3f317217, v25
	v_cmp_lt_f32_e64 s[14:15], |v25|, s4
	s_nop 1
	v_cndmask_b32_e64 v25, v25, v47, s[14:15]
	v_med3_f32 v47, v56, s17, v231
	v_mul_f32_e32 v47, 0xbfb8aa3b, v47
	v_exp_f32_e32 v60, v47
	s_nop 0
	v_add_f32_e32 v47, 1.0, v60
	v_rcp_f32_e32 v64, v47
	v_med3_f32 v47, v57, s17, v231
	v_mul_f32_e32 v47, 0xbfb8aa3b, v47
	v_exp_f32_e32 v61, v47
	v_fma_f32 v26, v64, v66, v26
	v_add_f32_e32 v47, 1.0, v61
	v_rcp_f32_e32 v65, v47
	v_log_f32_e32 v26, v26
	v_fmac_f32_e32 v27, v65, v67
	v_pk_mul_f32 v[60:61], v[60:61], v[64:65]
	v_mul_f32_e32 v47, 0x3f317217, v26
	v_fma_f32 v47, v26, s1, -v47
	v_fmac_f32_e32 v47, 0x3377d1cf, v26
	v_fmac_f32_e32 v47, 0x3f317217, v26
	v_cmp_lt_f32_e64 s[14:15], |v26|, s4
	v_pk_mul_f32 v[60:61], v[60:61], v[66:67]
	s_nop 0
	v_cndmask_b32_e64 v26, v26, v47, s[14:15]
	v_log_f32_e32 v27, v27
	s_nop 0
	v_mul_f32_e32 v47, 0x3f317217, v27
	v_fma_f32 v47, v27, s1, -v47
	v_fmac_f32_e32 v47, 0x3377d1cf, v27
	v_fmac_f32_e32 v47, 0x3f317217, v27
	v_cmp_lt_f32_e64 s[14:15], |v27|, s4
	s_nop 1
	v_cndmask_b32_e64 v27, v27, v47, s[14:15]
	global_store_dwordx4 v[42:43], v[28:31], off
	global_store_dwordx4 v[42:43], v[24:27], off offset:16
	s_nop 0
	v_lshl_add_u64 v[28:29], v[40:41], 1, v[36:37]
	v_cvt_pk_bf16_f32 v24, v50, v51
	v_cvt_pk_bf16_f32 v25, v58, v59
	v_cvt_pk_bf16_f32 v26, v62, v63
	v_cvt_pk_bf16_f32 v27, v60, v61
	global_store_dwordx4 v[28:29], v[24:27], off

.LBB0_986:
	s_andn2_b64 vcc, exec, s[14:15]
	s_cbranch_vccnz .LBB0_988
	v_lshl_add_u32 v48, s95, 7, v194
	v_ashrrev_i32_e32 v49, 31, v48
	v_lshlrev_b64 v[52:53], 2, v[48:49]
	v_lshl_add_u64 v[20:21], s[80:81], 0, v[52:53]
	global_load_dwordx4 v[16:19], v[20:21], off offset:16
	s_nop 0
	global_load_dwordx4 v[20:23], v[20:21], off
	s_mov_b32 s17, 0xc2700000
	v_med3_f32 v33, v24, s17, v231
	v_mul_f32_e32 v33, 0xbfb8aa3b, v33
	v_exp_f32_e32 v54, v33
	s_mov_b32 s1, 0x3f317217
	v_lshl_add_u64 v[38:39], v[38:39], 0, v[52:53]
	v_add_f32_e32 v33, 1.0, v54
	v_rcp_f32_e32 v56, v33
	v_med3_f32 v33, v25, s17, v231
	v_mul_f32_e32 v33, 0xbfb8aa3b, v33
	v_exp_f32_e32 v55, v33
	s_waitcnt vmcnt(0)
	v_pk_add_f32 v[62:63], v[16:17], 1.0 op_sel_hi:[1,0] neg_lo:[1,0] neg_hi:[1,0]
	v_pk_add_f32 v[58:59], v[20:21], 1.0 op_sel_hi:[1,0] neg_lo:[1,0] neg_hi:[1,0]
	v_add_f32_e32 v33, 1.0, v55
	v_fma_f32 v20, v56, v58, v20
	v_rcp_f32_e32 v57, v33
	v_pk_add_f32 v[60:61], v[22:23], 1.0 op_sel_hi:[1,0] neg_lo:[1,0] neg_hi:[1,0]
	v_log_f32_e32 v20, v20
	v_fma_f32 v21, v57, v59, v21
	v_pk_mul_f32 v[54:55], v[54:55], v[56:57]
	v_pk_add_f32 v[64:65], v[18:19], 1.0 op_sel_hi:[1,0] neg_lo:[1,0] neg_hi:[1,0]
	v_mul_f32_e32 v33, 0x3f317217, v20
	v_fma_f32 v33, v20, s1, -v33
	v_fmac_f32_e32 v33, 0x3377d1cf, v20
	v_fmac_f32_e32 v33, 0x3f317217, v20
	v_cmp_lt_f32_e64 s[14:15], |v20|, s4
	v_pk_mul_f32 v[54:55], v[54:55], v[58:59]
	s_nop 0
	v_cndmask_b32_e64 v20, v20, v33, s[14:15]
	v_log_f32_e32 v21, v21
	s_nop 0
	v_mul_f32_e32 v33, 0x3f317217, v21
	v_fma_f32 v33, v21, s1, -v33
	v_fmac_f32_e32 v33, 0x3377d1cf, v21
	v_fmac_f32_e32 v33, 0x3f317217, v21
	v_cmp_lt_f32_e64 s[14:15], |v21|, s4
	s_nop 1
	v_cndmask_b32_e64 v21, v21, v33, s[14:15]
	v_med3_f32 v33, v26, s17, v231
	v_mul_f32_e32 v33, 0xbfb8aa3b, v33
	v_exp_f32_e32 v56, v33
	s_nop 0
	v_add_f32_e32 v33, 1.0, v56
	v_rcp_f32_e32 v58, v33
	v_med3_f32 v33, v27, s17, v231
	v_mul_f32_e32 v33, 0xbfb8aa3b, v33
	v_exp_f32_e32 v57, v33
	v_fma_f32 v22, v58, v60, v22
	v_add_f32_e32 v33, 1.0, v57
	v_rcp_f32_e32 v59, v33
	v_log_f32_e32 v22, v22
	v_fmac_f32_e32 v23, v59, v61
	v_pk_mul_f32 v[56:57], v[56:57], v[58:59]
	v_mul_f32_e32 v33, 0x3f317217, v22
	v_fma_f32 v33, v22, s1, -v33
	v_fmac_f32_e32 v33, 0x3377d1cf, v22
	v_fmac_f32_e32 v33, 0x3f317217, v22
	v_cmp_lt_f32_e64 s[14:15], |v22|, s4
	v_pk_mul_f32 v[56:57], v[56:57], v[60:61]
	s_nop 0
	v_cndmask_b32_e64 v22, v22, v33, s[14:15]
	v_log_f32_e32 v23, v23
	s_nop 0
	v_mul_f32_e32 v33, 0x3f317217, v23
	v_fma_f32 v33, v23, s1, -v33
	v_fmac_f32_e32 v33, 0x3377d1cf, v23
	v_fmac_f32_e32 v33, 0x3f317217, v23
	v_cmp_lt_f32_e64 s[14:15], |v23|, s4
	s_nop 1
	v_cndmask_b32_e64 v23, v23, v33, s[14:15]
	v_med3_f32 v33, v44, s17, v231
	v_mul_f32_e32 v33, 0xbfb8aa3b, v33
	v_exp_f32_e32 v60, v33
	s_nop 0
	v_add_f32_e32 v33, 1.0, v60
	v_rcp_f32_e32 v58, v33
	v_med3_f32 v33, v45, s17, v231
	v_mul_f32_e32 v33, 0xbfb8aa3b, v33
	v_exp_f32_e32 v61, v33
	v_fma_f32 v16, v58, v62, v16
	v_add_f32_e32 v33, 1.0, v61
	v_rcp_f32_e32 v59, v33
	v_log_f32_e32 v16, v16
	v_fma_f32 v17, v59, v63, v17
	v_pk_mul_f32 v[60:61], v[60:61], v[58:59]
	v_mul_f32_e32 v33, 0x3f317217, v16
	v_fma_f32 v33, v16, s1, -v33
	v_fmac_f32_e32 v33, 0x3377d1cf, v16
	v_fmac_f32_e32 v33, 0x3f317217, v16
	v_cmp_lt_f32_e64 s[14:15], |v16|, s4
	v_pk_mul_f32 v[60:61], v[60:61], v[62:63]
	s_nop 0
	v_cndmask_b32_e64 v16, v16, v33, s[14:15]
	v_log_f32_e32 v17, v17
	s_nop 0
	v_mul_f32_e32 v33, 0x3f317217, v17
	v_fma_f32 v33, v17, s1, -v33
	v_fmac_f32_e32 v33, 0x3377d1cf, v17
	v_fmac_f32_e32 v33, 0x3f317217, v17
	v_cmp_lt_f32_e64 s[14:15], |v17|, s4
	s_nop 1
	v_cndmask_b32_e64 v17, v17, v33, s[14:15]
	v_med3_f32 v33, v46, s17, v231
	v_mul_f32_e32 v33, 0xbfb8aa3b, v33
	v_exp_f32_e32 v58, v33
	s_nop 0
	v_add_f32_e32 v33, 1.0, v58
	v_rcp_f32_e32 v62, v33
	v_med3_f32 v33, v47, s17, v231
	v_mul_f32_e32 v33, 0xbfb8aa3b, v33
	v_exp_f32_e32 v59, v33
	v_fma_f32 v18, v62, v64, v18
	v_add_f32_e32 v33, 1.0, v59
	v_rcp_f32_e32 v63, v33
	v_log_f32_e32 v18, v18
	v_fmac_f32_e32 v19, v63, v65
	v_pk_mul_f32 v[58:59], v[58:59], v[62:63]
	v_mul_f32_e32 v33, 0x3f317217, v18
	v_fma_f32 v33, v18, s1, -v33
	v_fmac_f32_e32 v33, 0x3377d1cf, v18
	v_fmac_f32_e32 v33, 0x3f317217, v18
	v_cmp_lt_f32_e64 s[14:15], |v18|, s4
	v_pk_mul_f32 v[58:59], v[58:59], v[64:65]
	s_nop 0
	v_cndmask_b32_e64 v18, v18, v33, s[14:15]
	v_log_f32_e32 v19, v19
	s_nop 0
	v_mul_f32_e32 v33, 0x3f317217, v19
	v_fma_f32 v33, v19, s1, -v33
	v_fmac_f32_e32 v33, 0x3377d1cf, v19
	v_fmac_f32_e32 v33, 0x3f317217, v19
	v_cmp_lt_f32_e64 s[14:15], |v19|, s4
	s_nop 1
	v_cndmask_b32_e64 v19, v19, v33, s[14:15]
	global_store_dwordx4 v[38:39], v[20:23], off
	global_store_dwordx4 v[38:39], v[16:19], off offset:16
	s_nop 0
	v_lshl_add_u64 v[20:21], v[48:49], 1, v[36:37]
	v_cvt_pk_bf16_f32 v16, v54, v55
	v_cvt_pk_bf16_f32 v17, v56, v57
	v_cvt_pk_bf16_f32 v18, v60, v61
	v_cvt_pk_bf16_f32 v19, v58, v59
	global_store_dwordx4 v[20:21], v[16:19], off
	s_mov_b64 s[14:15], 0
	s_branch .LBB0_1005

.LBB0_1021:
	s_andn2_b64 vcc, exec, s[10:11]
	s_cbranch_vccnz .LBB0_1023
	v_lshl_add_u32 v24, s93, 8, v194
	v_ashrrev_i32_e32 v25, 31, v24
	v_lshlrev_b64 v[26:27], 2, v[24:25]
	v_lshl_add_u64 v[12:13], s[80:81], 0, v[26:27]
	global_load_dwordx4 v[8:11], v[12:13], off offset:16
	s_nop 0
	global_load_dwordx4 v[12:15], v[12:13], off
	s_mov_b32 s14, 0xc2700000
	v_med3_f32 v31, v28, s14, v231
	v_mul_f32_e32 v31, 0xbfb8aa3b, v31
	v_exp_f32_e32 v34, v31
	s_mov_b32 s1, 0x3f317217
	v_lshl_add_u64 v[26:27], v[22:23], 0, v[26:27]
	v_add_f32_e32 v31, 1.0, v34
	v_rcp_f32_e32 v42, v31
	v_med3_f32 v31, v29, s14, v231
	v_mul_f32_e32 v31, 0xbfb8aa3b, v31
	v_exp_f32_e32 v35, v31
	s_waitcnt vmcnt(0)
	v_pk_add_f32 v[48:49], v[8:9], 1.0 op_sel_hi:[1,0] neg_lo:[1,0] neg_hi:[1,0]
	v_pk_add_f32 v[44:45], v[12:13], 1.0 op_sel_hi:[1,0] neg_lo:[1,0] neg_hi:[1,0]
	v_add_f32_e32 v31, 1.0, v35
	v_fma_f32 v12, v42, v44, v12
	v_rcp_f32_e32 v43, v31
	v_pk_add_f32 v[46:47], v[14:15], 1.0 op_sel_hi:[1,0] neg_lo:[1,0] neg_hi:[1,0]
	v_log_f32_e32 v12, v12
	v_fma_f32 v13, v43, v45, v13
	v_pk_mul_f32 v[34:35], v[34:35], v[42:43]
	v_pk_add_f32 v[50:51], v[10:11], 1.0 op_sel_hi:[1,0] neg_lo:[1,0] neg_hi:[1,0]
	v_mul_f32_e32 v31, 0x3f317217, v12
	v_fma_f32 v31, v12, s1, -v31
	v_fmac_f32_e32 v31, 0x3377d1cf, v12
	v_fmac_f32_e32 v31, 0x3f317217, v12
	v_cmp_lt_f32_e64 s[10:11], |v12|, s4
	v_pk_mul_f32 v[34:35], v[34:35], v[44:45]
	s_nop 0
	v_cndmask_b32_e64 v12, v12, v31, s[10:11]
	v_log_f32_e32 v13, v13
	s_nop 0
	v_mul_f32_e32 v31, 0x3f317217, v13
	v_fma_f32 v31, v13, s1, -v31
	v_fmac_f32_e32 v31, 0x3377d1cf, v13
	v_fmac_f32_e32 v31, 0x3f317217, v13
	v_cmp_lt_f32_e64 s[10:11], |v13|, s4
	s_nop 1
	v_cndmask_b32_e64 v13, v13, v31, s[10:11]
	v_med3_f32 v31, v36, s14, v231
	v_mul_f32_e32 v31, 0xbfb8aa3b, v31
	v_exp_f32_e32 v42, v31
	s_nop 0
	v_add_f32_e32 v31, 1.0, v42
	v_rcp_f32_e32 v44, v31
	v_med3_f32 v31, v37, s14, v231
	v_mul_f32_e32 v31, 0xbfb8aa3b, v31
	v_exp_f32_e32 v43, v31
	v_fma_f32 v14, v44, v46, v14
	v_add_f32_e32 v31, 1.0, v43
	v_rcp_f32_e32 v45, v31
	v_log_f32_e32 v14, v14
	v_fmac_f32_e32 v15, v45, v47
	v_pk_mul_f32 v[42:43], v[42:43], v[44:45]
	v_mul_f32_e32 v31, 0x3f317217, v14
	v_fma_f32 v31, v14, s1, -v31
	v_fmac_f32_e32 v31, 0x3377d1cf, v14
	v_fmac_f32_e32 v31, 0x3f317217, v14
	v_cmp_lt_f32_e64 s[10:11], |v14|, s4
	v_pk_mul_f32 v[42:43], v[42:43], v[46:47]
	s_nop 0
	v_cndmask_b32_e64 v14, v14, v31, s[10:11]
	v_log_f32_e32 v15, v15
	s_nop 0
	v_mul_f32_e32 v31, 0x3f317217, v15
	v_fma_f32 v31, v15, s1, -v31
	v_fmac_f32_e32 v31, 0x3377d1cf, v15
	v_fmac_f32_e32 v31, 0x3f317217, v15
	v_cmp_lt_f32_e64 s[10:11], |v15|, s4
	s_nop 1
	v_cndmask_b32_e64 v15, v15, v31, s[10:11]
	v_med3_f32 v31, v38, s14, v231
	v_mul_f32_e32 v31, 0xbfb8aa3b, v31
	v_exp_f32_e32 v46, v31
	s_nop 0
	v_add_f32_e32 v31, 1.0, v46
	v_rcp_f32_e32 v44, v31
	v_med3_f32 v31, v39, s14, v231
	v_mul_f32_e32 v31, 0xbfb8aa3b, v31
	v_exp_f32_e32 v47, v31
	v_fma_f32 v8, v44, v48, v8
	v_add_f32_e32 v31, 1.0, v47
	v_rcp_f32_e32 v45, v31
	v_log_f32_e32 v8, v8
	v_fma_f32 v9, v45, v49, v9
	v_pk_mul_f32 v[46:47], v[46:47], v[44:45]
	v_mul_f32_e32 v31, 0x3f317217, v8
	v_fma_f32 v31, v8, s1, -v31
	v_fmac_f32_e32 v31, 0x3377d1cf, v8
	v_fmac_f32_e32 v31, 0x3f317217, v8
	v_cmp_lt_f32_e64 s[10:11], |v8|, s4
	v_pk_mul_f32 v[46:47], v[46:47], v[48:49]
	s_nop 0
	v_cndmask_b32_e64 v8, v8, v31, s[10:11]
	v_log_f32_e32 v9, v9
	s_nop 0
	v_mul_f32_e32 v31, 0x3f317217, v9
	v_fma_f32 v31, v9, s1, -v31
	v_fmac_f32_e32 v31, 0x3377d1cf, v9
	v_fmac_f32_e32 v31, 0x3f317217, v9
	v_cmp_lt_f32_e64 s[10:11], |v9|, s4
	s_nop 1
	v_cndmask_b32_e64 v9, v9, v31, s[10:11]
	v_med3_f32 v31, v40, s14, v231
	v_mul_f32_e32 v31, 0xbfb8aa3b, v31
	v_exp_f32_e32 v44, v31
	s_nop 0
	v_add_f32_e32 v31, 1.0, v44
	v_rcp_f32_e32 v48, v31
	v_med3_f32 v31, v41, s14, v231
	v_mul_f32_e32 v31, 0xbfb8aa3b, v31
	v_exp_f32_e32 v45, v31
	v_fma_f32 v10, v48, v50, v10
	v_add_f32_e32 v31, 1.0, v45
	v_rcp_f32_e32 v49, v31
	v_log_f32_e32 v10, v10
	v_fmac_f32_e32 v11, v49, v51
	v_pk_mul_f32 v[44:45], v[44:45], v[48:49]
	v_mul_f32_e32 v31, 0x3f317217, v10
	v_fma_f32 v31, v10, s1, -v31
	v_fmac_f32_e32 v31, 0x3377d1cf, v10
	v_fmac_f32_e32 v31, 0x3f317217, v10
	v_cmp_lt_f32_e64 s[10:11], |v10|, s4
	v_pk_mul_f32 v[44:45], v[44:45], v[50:51]
	s_nop 0
	v_cndmask_b32_e64 v10, v10, v31, s[10:11]
	v_log_f32_e32 v11, v11
	s_nop 0
	v_mul_f32_e32 v31, 0x3f317217, v11
	v_fma_f32 v31, v11, s1, -v31
	v_fmac_f32_e32 v31, 0x3377d1cf, v11
	v_fmac_f32_e32 v31, 0x3f317217, v11
	v_cmp_lt_f32_e64 s[10:11], |v11|, s4
	s_nop 1
	v_cndmask_b32_e64 v11, v11, v31, s[10:11]
	global_store_dwordx4 v[26:27], v[12:15], off
	global_store_dwordx4 v[26:27], v[8:11], off offset:16
	s_nop 0
	v_lshl_add_u64 v[12:13], v[24:25], 1, v[20:21]
	v_cvt_pk_bf16_f32 v8, v34, v35
	v_cvt_pk_bf16_f32 v9, v42, v43
	v_cvt_pk_bf16_f32 v10, v46, v47
	v_cvt_pk_bf16_f32 v11, v44, v45
	global_store_dwordx4 v[12:13], v[8:11], off

.LBB0_1053:
	s_andn2_b64 vcc, exec, s[10:11]
	s_cbranch_vccnz .LBB0_1055
	v_lshl_add_u32 v32, s95, 7, v194
	v_ashrrev_i32_e32 v33, 31, v32
	v_lshlrev_b64 v[36:37], 2, v[32:33]
	v_lshl_add_u64 v[4:5], s[80:81], 0, v[36:37]
	global_load_dwordx4 v[0:3], v[4:5], off offset:16
	s_nop 0
	global_load_dwordx4 v[4:7], v[4:5], off
	s_mov_b32 s12, 0xc2700000
	v_med3_f32 v17, v8, s12, v231
	v_mul_f32_e32 v17, 0xbfb8aa3b, v17
	v_exp_f32_e32 v38, v17
	s_mov_b32 s1, 0x3f317217
	v_lshl_add_u64 v[22:23], v[22:23], 0, v[36:37]
	v_add_f32_e32 v17, 1.0, v38
	v_rcp_f32_e32 v40, v17
	v_med3_f32 v17, v9, s12, v231
	v_mul_f32_e32 v17, 0xbfb8aa3b, v17
	v_exp_f32_e32 v39, v17
	s_waitcnt vmcnt(0)
	v_pk_add_f32 v[46:47], v[0:1], 1.0 op_sel_hi:[1,0] neg_lo:[1,0] neg_hi:[1,0]
	v_pk_add_f32 v[42:43], v[4:5], 1.0 op_sel_hi:[1,0] neg_lo:[1,0] neg_hi:[1,0]
	v_add_f32_e32 v17, 1.0, v39
	v_fma_f32 v4, v40, v42, v4
	v_rcp_f32_e32 v41, v17
	v_pk_add_f32 v[44:45], v[6:7], 1.0 op_sel_hi:[1,0] neg_lo:[1,0] neg_hi:[1,0]
	v_log_f32_e32 v4, v4
	v_fma_f32 v5, v41, v43, v5
	v_pk_mul_f32 v[38:39], v[38:39], v[40:41]
	v_pk_add_f32 v[48:49], v[2:3], 1.0 op_sel_hi:[1,0] neg_lo:[1,0] neg_hi:[1,0]
	v_mul_f32_e32 v17, 0x3f317217, v4
	v_fma_f32 v17, v4, s1, -v17
	v_fmac_f32_e32 v17, 0x3377d1cf, v4
	v_fmac_f32_e32 v17, 0x3f317217, v4
	v_cmp_lt_f32_e64 s[10:11], |v4|, s4
	v_pk_mul_f32 v[38:39], v[38:39], v[42:43]
	s_nop 0
	v_cndmask_b32_e64 v4, v4, v17, s[10:11]
	v_log_f32_e32 v5, v5
	s_nop 0
	v_mul_f32_e32 v17, 0x3f317217, v5
	v_fma_f32 v17, v5, s1, -v17
	v_fmac_f32_e32 v17, 0x3377d1cf, v5
	v_fmac_f32_e32 v17, 0x3f317217, v5
	v_cmp_lt_f32_e64 s[10:11], |v5|, s4
	s_nop 1
	v_cndmask_b32_e64 v5, v5, v17, s[10:11]
	v_med3_f32 v17, v10, s12, v231
	v_mul_f32_e32 v17, 0xbfb8aa3b, v17
	v_exp_f32_e32 v40, v17
	s_nop 0
	v_add_f32_e32 v17, 1.0, v40
	v_rcp_f32_e32 v42, v17
	v_med3_f32 v17, v11, s12, v231
	v_mul_f32_e32 v17, 0xbfb8aa3b, v17
	v_exp_f32_e32 v41, v17
	v_fma_f32 v6, v42, v44, v6
	v_add_f32_e32 v17, 1.0, v41
	v_rcp_f32_e32 v43, v17
	v_log_f32_e32 v6, v6
	v_fmac_f32_e32 v7, v43, v45
	v_pk_mul_f32 v[40:41], v[40:41], v[42:43]
	v_mul_f32_e32 v17, 0x3f317217, v6
	v_fma_f32 v17, v6, s1, -v17
	v_fmac_f32_e32 v17, 0x3377d1cf, v6
	v_fmac_f32_e32 v17, 0x3f317217, v6
	v_cmp_lt_f32_e64 s[10:11], |v6|, s4
	v_pk_mul_f32 v[40:41], v[40:41], v[44:45]
	s_nop 0
	v_cndmask_b32_e64 v6, v6, v17, s[10:11]
	v_log_f32_e32 v7, v7
	s_nop 0
	v_mul_f32_e32 v17, 0x3f317217, v7
	v_fma_f32 v17, v7, s1, -v17
	v_fmac_f32_e32 v17, 0x3377d1cf, v7
	v_fmac_f32_e32 v17, 0x3f317217, v7
	v_cmp_lt_f32_e64 s[10:11], |v7|, s4
	s_nop 1
	v_cndmask_b32_e64 v7, v7, v17, s[10:11]
	v_med3_f32 v17, v28, s12, v231
	v_mul_f32_e32 v17, 0xbfb8aa3b, v17
	v_exp_f32_e32 v44, v17
	s_nop 0
	v_add_f32_e32 v17, 1.0, v44
	v_rcp_f32_e32 v42, v17
	v_med3_f32 v17, v29, s12, v231
	v_mul_f32_e32 v17, 0xbfb8aa3b, v17
	v_exp_f32_e32 v45, v17
	v_fma_f32 v0, v42, v46, v0
	v_add_f32_e32 v17, 1.0, v45
	v_rcp_f32_e32 v43, v17
	v_log_f32_e32 v0, v0
	v_fma_f32 v1, v43, v47, v1
	v_pk_mul_f32 v[44:45], v[44:45], v[42:43]
	v_mul_f32_e32 v17, 0x3f317217, v0
	v_fma_f32 v17, v0, s1, -v17
	v_fmac_f32_e32 v17, 0x3377d1cf, v0
	v_fmac_f32_e32 v17, 0x3f317217, v0
	v_cmp_lt_f32_e64 s[10:11], |v0|, s4
	v_pk_mul_f32 v[44:45], v[44:45], v[46:47]
	s_nop 0
	v_cndmask_b32_e64 v0, v0, v17, s[10:11]
	v_log_f32_e32 v1, v1
	s_nop 0
	v_mul_f32_e32 v17, 0x3f317217, v1
	v_fma_f32 v17, v1, s1, -v17
	v_fmac_f32_e32 v17, 0x3377d1cf, v1
	v_fmac_f32_e32 v17, 0x3f317217, v1
	v_cmp_lt_f32_e64 s[10:11], |v1|, s4
	s_nop 1
	v_cndmask_b32_e64 v1, v1, v17, s[10:11]
	v_med3_f32 v17, v30, s12, v231
	v_mul_f32_e32 v17, 0xbfb8aa3b, v17
	v_exp_f32_e32 v42, v17
	s_nop 0
	v_add_f32_e32 v17, 1.0, v42
	v_rcp_f32_e32 v46, v17
	v_med3_f32 v17, v31, s12, v231
	v_mul_f32_e32 v17, 0xbfb8aa3b, v17
	v_exp_f32_e32 v43, v17
	v_fma_f32 v2, v46, v48, v2
	v_add_f32_e32 v17, 1.0, v43
	v_rcp_f32_e32 v47, v17
	v_log_f32_e32 v2, v2
	v_fmac_f32_e32 v3, v47, v49
	v_pk_mul_f32 v[42:43], v[42:43], v[46:47]
	v_mul_f32_e32 v17, 0x3f317217, v2
	v_fma_f32 v17, v2, s1, -v17
	v_fmac_f32_e32 v17, 0x3377d1cf, v2
	v_fmac_f32_e32 v17, 0x3f317217, v2
	v_cmp_lt_f32_e64 s[10:11], |v2|, s4
	v_pk_mul_f32 v[42:43], v[42:43], v[48:49]
	s_nop 0
	v_cndmask_b32_e64 v2, v2, v17, s[10:11]
	v_log_f32_e32 v3, v3
	s_nop 0
	v_mul_f32_e32 v17, 0x3f317217, v3
	v_fma_f32 v17, v3, s1, -v17
	v_fmac_f32_e32 v17, 0x3377d1cf, v3
	v_fmac_f32_e32 v17, 0x3f317217, v3
	v_cmp_lt_f32_e64 s[10:11], |v3|, s4
	s_nop 1
	v_cndmask_b32_e64 v3, v3, v17, s[10:11]
	global_store_dwordx4 v[22:23], v[4:7], off
	global_store_dwordx4 v[22:23], v[0:3], off offset:16
	s_nop 0
	v_lshl_add_u64 v[4:5], v[32:33], 1, v[20:21]
	v_cvt_pk_bf16_f32 v0, v38, v39
	v_cvt_pk_bf16_f32 v1, v40, v41
	v_cvt_pk_bf16_f32 v2, v44, v45
	v_cvt_pk_bf16_f32 v3, v42, v43
	global_store_dwordx4 v[4:5], v[0:3], off
	s_mov_b64 s[10:11], 0
	s_branch .LBB0_1072
